# first K-loop iteration of each unit peeled: its first two counted waits are counted past the previous unit epilogue stores so the store drain overlaps the first phases; phase prologue drains its own s
# baseline (speedup 1.0000x reference)
; #define PG8_STAGE(bufoff, gbase, voff) do { _Pragma("unroll") for (int _i = 0; _i < 2; ++_i) \
;         __builtin_amdgcn_global_load_lds((const unsigned*)((const char*)(gbase) + (voff)[_i]), (LAS unsigned*)(lds + (bufoff) + ldsw + _i * 8192), 16, 0, 0); } while (0)
; #define PG8_WAIT_V(n) asm volatile("s_waitcnt vmcnt(" #n ")" ::: "memory")
; #define PG8_BAR __builtin_amdgcn_s_barrier()
; template <int MODE> __device__ __forceinline__ void gemm_phase(LAS unsigned char* lds, const GD& g, const int tid) {
;     ...
;     const int wid = __builtin_amdgcn_readfirstlane(tid >> 6), lane = tid & 63, wr = wid >> 2, wc = wid & 3, fr = lane & 15, fq = lane >> 4;
;     const int K = g.K, nt = K / BK;
;     constexpr bool perm = MODE != EP_RES;
;     unsigned voffA[2], voffB[2];
; #pragma unroll
;     for (int i = 0; i < 2; ++i) { int R, C; stage_rc(tid * 16 + i * 8192, R, C); const int Rb = perm ? ((R & ~31) + perm32(R & 31)) : R;
;         voffA[i] = (unsigned)(R * g.lda + C) * 2u; voffB[i] = (unsigned)(Rb * g.ldb + C) * 2u; }
;     const size_t kstA = (size_t)g.kstA, kstB = (size_t)g.kstB;
;     const size_t hsA = (size_t)HALF * g.lda * 2, hsB = (size_t)HALF * g.ldb * 2;
;     const unsigned ldsw = (unsigned)wid * 1024u;
;     const int aoff = lds_byte(wr * 64 + fr, fq * 8), boff = lds_byte(wc * 32 + fr, fq * 8);
;     ...
;     Unit cur, nxt; int ui = 0;
;     if (!gd_next(g, 0, cur)) return;
;     f32x4 acc[2][2][4][2];
; #pragma unroll
;     for (int a = 0; a < 2; ++a)
; #pragma unroll
;         for (int b = 0; b < 2; ++b)
; #pragma unroll
;             for (int m = 0; m < 4; ++m)
; #pragma unroll
;                 for (int n = 0; n < 2; ++n) acc[a][b][m][n] = (f32x4){0.f, 0.f, 0.f, 0.f};
;     float rsv[2][4] = {{0.f, 0.f, 0.f, 0.f}, {0.f, 0.f, 0.f, 0.f}}; rsv_load(rsv, g, cur, wr, fr);
;     bf16x8 At[4][2], B0[2][2], B1[2][2];
;     const char* cA = cur.A; const char* cB = cur.B;
;     PG8_STAGE(PG8_SB(0, 0), cB, voffB); PG8_STAGE(PG8_SB(0, 1), cB + hsB, voffB); PG8_STAGE(PG8_SA(0, 0), cA, voffA); PG8_STAGE(PG8_SA(0, 1), cA + hsA, voffA);
;     if (wr == 1) PG8_BAR;
;     PG8_WAIT_V(2); PG8_BAR;
;     PG8_STAGE(PG8_SB(1, 0), cB + kstB, voffB); PG8_STAGE(PG8_SA(1, 0), cA + kstA, voffA); PG8_STAGE(PG8_SB(1, 1), cB + hsB + kstB, voffB);
;     PG8_WAIT_V(6); PG8_BAR;
.LBB0_102:
	s_ashr_i32 s11, s56, 31
	s_lshr_b32 s11, s11, 26
	v_lshrrev_b32_e32 v8, 1, v194
	s_add_i32 s11, s56, s11
	v_and_b32_e32 v10, 24, v8
	s_lshl_b32 s5, s5, 5
	s_ashr_i32 s17, s11, 6
	v_lshlrev_b32_e32 v8, 6, v144
	v_lshlrev_b32_e32 v9, 1, v10
	s_movk_i32 s11, 0x3c0
	v_lshlrev_b32_e32 v11, 2, v144
	s_and_b32 s12, s5, 0x60
	s_ashr_i32 s21, s20, 31
	s_ashr_i32 s23, s22, 31
	v_and_or_b32 v8, v8, s11, v9
	s_lshl_b32 s10, s10, 13
	v_and_b32_e32 v11, 32, v11
	s_lshl_b32 s13, s12, 7
	v_bitop3_b32 v11, v8, s10, v11 bitop3:0xde
	s_add_u32 s10, s50, s22
	v_mov_b32_e32 v133, v0
	s_addc_u32 s11, s51, s23
	v_lshl_or_b32 v12, v7, 6, v9
	s_add_i32 m0, s27, 0x18000
	v_lshl_add_u64 v[8:9], s[10:11], 0, v[132:133]
	v_mov_b32_e32 v137, v0
	s_waitcnt vmcnt(2)
	s_barrier
	global_load_lds_dwordx4 v[8:9], off
	s_add_i32 m0, s27, 0x1a000
	v_lshl_add_u64 v[8:9], s[10:11], 0, v[136:137]
	s_add_u32 s10, s6, s20
	v_mov_b32_e32 v131, v0
	s_addc_u32 s11, s7, s21
	s_add_i32 s58, s27, 0x8000
	s_add_i32 s59, s27, 0xa000
	v_mov_b32_e32 v135, v0
	global_load_lds_dwordx4 v[8:9], off
	v_lshl_add_u64 v[8:9], s[10:11], 0, v[130:131]
	s_mov_b32 m0, s58
	s_add_u32 s2, s2, s22
	global_load_lds_dwordx4 v[8:9], off
	v_lshl_add_u64 v[8:9], s[10:11], 0, v[134:135]
	s_mov_b32 m0, s59
	s_addc_u32 s3, s3, s23
	global_load_lds_dwordx4 v[8:9], off
	s_add_i32 m0, s27, 0x1c000
	v_lshl_add_u64 v[8:9], s[2:3], 0, v[132:133]
	global_load_lds_dwordx4 v[8:9], off
	s_add_i32 m0, s27, 0x1e000
	s_cmp_gt_i32 s56, 63
	s_cselect_b64 s[60:61], -1, 0
	s_add_i32 s69, s17, -2
	v_lshl_add_u64 v[8:9], s[2:3], 0, v[136:137]
	s_cmpk_lt_u32 s4, 0x100
	v_readlane_b32 s11, v254, 33
	v_readlane_b32 s10, v255, 9
	v_readlane_b32 s2, v254, 60
	s_cselect_b64 s[62:63], -1, 0
	s_mul_i32 s14, s10, s11
	s_cmp_lg_u32 s2, 1
	s_mul_i32 s35, s2, s14
	s_cselect_b64 s[2:3], -1, 0
	v_writelane_b32 v255, s2, 16
	s_cmp_eq_u32 s11, 16
	global_load_lds_dwordx4 v[8:9], off
	v_writelane_b32 v255, s3, 17
	s_cselect_b64 s[2:3], -1, 0
	s_and_b32 s4, s10, 3
	s_cmp_eq_u32 s4, 0
	s_cselect_b64 s[4:5], -1, 0
	s_and_b64 s[2:3], s[2:3], s[4:5]
	s_and_b32 s4, s81, 7
	s_cmp_eq_u32 s4, 0
	s_cselect_b64 s[4:5], -1, 0
	s_and_b64 s[2:3], s[2:3], s[4:5]
	v_writelane_b32 v255, s2, 18
	s_lshl_b32 s26, s10, 3
	v_lshlrev_b32_e32 v7, 2, v7
	v_writelane_b32 v255, s3, 19
	s_xor_b64 s[2:3], s[2:3], -1
	v_writelane_b32 v255, s2, 20
	v_and_b32_e32 v7, 32, v7
	v_bitop3_b32 v153, s13, v12, v7 bitop3:0xf6
	v_writelane_b32 v255, s3, 21
	s_and_b32 s2, s83, 7
	s_ashr_i32 s3, s81, 3
	s_mul_i32 s2, s3, s2
	s_lshr_b32 s3, s83, 3
	s_add_i32 s2, s2, s3
	s_abs_i32 s3, s81
	v_cvt_f32_u32_e32 v8, s3
	v_writelane_b32 v255, s2, 28
	s_ashr_i32 s2, s14, 31
	v_writelane_b32 v255, s2, 8
	v_rcp_iflag_f32_e32 v8, v8
	s_lshr_b32 s2, s2, 29
	s_sub_i32 s5, 0, s3
	s_add_i32 s2, s14, s2
	v_mul_f32_e32 v8, 0x4f7ffffe, v8
	v_cvt_u32_f32_e32 v8, v8
	s_ashr_i32 s4, s2, 3
	s_and_b32 s2, s2, -8
	s_sub_i32 s33, s14, s2
	v_readfirstlane_b32 s10, v8
	s_mul_i32 s5, s5, s10
	s_mul_hi_u32 s5, s10, s5
	v_writelane_b32 v255, s4, 32
	s_add_i32 s2, s4, 1
	s_abs_i32 s4, s35
	s_add_i32 s10, s10, s5
	s_mul_hi_u32 s5, s4, s10
	s_mul_i32 s5, s5, s3
	s_sub_i32 s4, s4, s5
	v_writelane_b32 v255, s2, 4
	s_ashr_i32 s2, s35, 31
	s_sub_i32 s5, s4, s3
	s_cmp_ge_u32 s4, s3
	s_cselect_b32 s4, s5, s4
	s_sub_i32 s5, s4, s3
	s_cmp_ge_u32 s4, s3
	s_cselect_b32 s3, s5, s4
	s_xor_b32 s3, s3, s2
	s_sub_i32 s2, s3, s2
	s_cmp_lg_u32 s2, 0
	s_cselect_b64 s[2:3], -1, 0
	v_writelane_b32 v255, s2, 33
	s_abs_i32 s4, s11
	s_abs_i32 s5, s26
	v_writelane_b32 v255, s3, 34
	s_abs_i32 s2, s14
	v_cvt_f32_u32_e32 v8, s2
	v_writelane_b32 v255, s14, 31
	v_writelane_b32 v255, s2, 25
	s_sub_i32 s2, 0, s2
	v_rcp_iflag_f32_e32 v7, v8
	v_cvt_f32_u32_e32 v8, s4
	s_abs_i32 s24, s79
	s_lshl_b64 s[86:87], s[22:23], 1
	v_mul_f32_e32 v7, 0x4f7ffffe, v7
	v_cvt_u32_f32_e32 v7, v7
	s_lshl_b64 s[92:93], s[20:21], 1
	s_waitcnt vmcnt(0)
	v_add_u32_e32 v4, v6, v4
	v_readfirstlane_b32 s3, v7
	v_rcp_iflag_f32_e32 v7, v8
	v_cvt_f32_u32_e32 v8, s5
	s_mul_i32 s2, s2, s3
	s_mul_hi_u32 s2, s3, s2
	v_mul_f32_e32 v7, 0x4f7ffffe, v7
	v_cvt_u32_f32_e32 v7, v7
	s_add_i32 s2, s3, s2
	v_writelane_b32 v255, s2, 23
	s_ashr_i32 s2, s11, 31
	v_readfirstlane_b32 s3, v7
	v_rcp_iflag_f32_e32 v7, v8
	v_cvt_f32_u32_e32 v8, s24
	v_writelane_b32 v255, s2, 36
	s_sub_i32 s2, 0, s4
	s_mul_i32 s2, s2, s3
	v_mul_f32_e32 v7, 0x4f7ffffe, v7
	s_mul_hi_u32 s2, s3, s2
	v_cvt_u32_f32_e32 v7, v7
	v_rcp_iflag_f32_e32 v8, v8
	v_writelane_b32 v255, s4, 35
	s_add_i32 s2, s3, s2
	v_writelane_b32 v255, s2, 37
	v_writelane_b32 v255, s26, 30
	s_ashr_i32 s2, s26, 31
	v_writelane_b32 v255, s2, 24
	s_sub_i32 s2, 0, s5
	v_readfirstlane_b32 s3, v7
	v_mul_f32_e32 v7, 0x4f7ffffe, v8
	s_mul_i32 s2, s2, s3
	v_cvt_u32_f32_e32 v155, v7
	s_mul_hi_u32 s2, s3, s2
	s_add_i32 s2, s3, s2
	v_writelane_b32 v255, s2, 27
	s_ashr_i32 s2, s79, 31
	v_writelane_b32 v255, s2, 2
	s_sub_i32 s3, 0, s24
	v_readfirstlane_b32 s2, v155
	s_mov_b32 s38, s3
	s_mul_i32 s3, s3, s2
	s_mul_hi_u32 s3, s2, s3
	s_add_i32 s2, s2, s3
	v_writelane_b32 v255, s2, 6
	s_add_u32 s2, s44, s20
	v_add_u32_e32 v1, v3, v1
	s_addc_u32 s3, s45, s21
	v_add_lshl_u32 v4, v4, v5, 1
	v_mov_b32_e32 v5, v0
	v_add_lshl_u32 v2, v1, v2, 1
	v_mov_b32_e32 v3, v0
	s_mov_b32 s82, 0
	v_or_b32_e32 v154, s12, v10
	s_mov_b32 s15, s5
	v_lshl_add_u64 v[138:139], s[2:3], 0, v[4:5]
	v_lshl_add_u64 v[140:141], s[2:3], 0, v[2:3]
	v_add_u32_e32 v156, 0, v11
	s_barrier
	s_branch .LBB0_105

; template <int MODE> __device__ __forceinline__ void gemm_phase(LAS unsigned char* lds, const GD& g, const int tid) {
;     ...
;         for (int t = 0; t < nt; t += 2) {
;             const bool last = (t == nt - 2);
;             const char* a1 = cA + (size_t)(t + 1) * kstA;
;             const char* a2 = last ? nA : cA + (size_t)(t + 2) * kstA; const char* b2 = last ? nB : cB + (size_t)(t + 2) * kstB;
;     ...
;         if (!has_next) break;
; #pragma unroll
;         for (int a = 0; a < 2; ++a)
; #pragma unroll
;             for (int b = 0; b < 2; ++b)
; #pragma unroll
;                 for (int m = 0; m < 4; ++m)
; #pragma unroll
;                     for (int n = 0; n < 2; ++n) acc[a][b][m][n] = (f32x4){0.f, 0.f, 0.f, 0.f};
;         cur = nxt; cA = nA; cB = nB; ++ui; rsv_load(rsv, g, cur, wr, fr);
.LBB0_122:
	s_andn2_b64 vcc, exec, s[60:61]
	s_cbranch_vccnz .LBB0_129
	s_and_b64 s[2:3], s[76:77], exec
	s_cselect_b32 s43, s95, s7
	s_cselect_b32 s42, s94, s6
	s_cselect_b32 s49, s79, s51
	s_cselect_b32 s48, s78, s50
	s_add_u32 s50, s50, s86
	v_mov_b32_e32 v2, 0
	s_addc_u32 s51, s51, s87
	s_mov_b32 s4, 0
	v_mov_b32_e32 v3, v2
	v_mov_b32_e32 v4, v2
	v_mov_b32_e32 v5, v2
	v_mov_b32_e32 v10, v2
	v_mov_b32_e32 v11, v2
	v_mov_b32_e32 v12, v2
	v_mov_b32_e32 v13, v2
	v_mov_b32_e32 v18, v2
	v_mov_b32_e32 v19, v2
	v_mov_b32_e32 v20, v2
	v_mov_b32_e32 v21, v2
	v_mov_b32_e32 v26, v2
	v_mov_b32_e32 v27, v2
	v_mov_b32_e32 v28, v2
	v_mov_b32_e32 v29, v2
	v_mov_b32_e32 v34, v2
	v_mov_b32_e32 v35, v2
	v_mov_b32_e32 v36, v2
	v_mov_b32_e32 v37, v2
	v_mov_b32_e32 v42, v2
	v_mov_b32_e32 v43, v2
	v_mov_b32_e32 v44, v2
	v_mov_b32_e32 v45, v2
	v_mov_b32_e32 v50, v2
	v_mov_b32_e32 v51, v2
	v_mov_b32_e32 v52, v2
	v_mov_b32_e32 v53, v2
	v_mov_b32_e32 v58, v2
	v_mov_b32_e32 v59, v2
	v_mov_b32_e32 v60, v2
	v_mov_b32_e32 v61, v2
	v_mov_b32_e32 v6, v2
	v_mov_b32_e32 v7, v2
	v_mov_b32_e32 v8, v2
	v_mov_b32_e32 v9, v2
	v_mov_b32_e32 v14, v2
	v_mov_b32_e32 v15, v2
	v_mov_b32_e32 v16, v2
	v_mov_b32_e32 v17, v2
	v_mov_b32_e32 v22, v2
	v_mov_b32_e32 v23, v2
	v_mov_b32_e32 v24, v2
	v_mov_b32_e32 v25, v2
	v_mov_b32_e32 v30, v2
	v_mov_b32_e32 v31, v2
	v_mov_b32_e32 v32, v2
	v_mov_b32_e32 v33, v2
	v_mov_b32_e32 v38, v2
	v_mov_b32_e32 v39, v2
	v_mov_b32_e32 v40, v2
	v_mov_b32_e32 v41, v2
	v_mov_b32_e32 v46, v2
	v_mov_b32_e32 v47, v2
	v_mov_b32_e32 v48, v2
	v_mov_b32_e32 v49, v2
	v_mov_b32_e32 v54, v2
	v_mov_b32_e32 v55, v2
	v_mov_b32_e32 v56, v2
	v_mov_b32_e32 v57, v2
	v_mov_b32_e32 v62, v2
	v_mov_b32_e32 v63, v2
	v_mov_b32_e32 v64, v2
	v_mov_b32_e32 v65, v2
	v_mov_b32_e32 v66, v2
	v_mov_b32_e32 v67, v2
	v_mov_b32_e32 v68, v2
	v_mov_b32_e32 v69, v2
	v_mov_b32_e32 v74, v2
	v_mov_b32_e32 v75, v2
	v_mov_b32_e32 v76, v2
	v_mov_b32_e32 v77, v2
	v_mov_b32_e32 v82, v2
	v_mov_b32_e32 v83, v2
	v_mov_b32_e32 v84, v2
	v_mov_b32_e32 v85, v2
	v_mov_b32_e32 v90, v2
	v_mov_b32_e32 v91, v2
	v_mov_b32_e32 v92, v2
	v_mov_b32_e32 v93, v2
	v_mov_b32_e32 v98, v2
	v_mov_b32_e32 v99, v2
	v_mov_b32_e32 v100, v2
	v_mov_b32_e32 v101, v2
	v_mov_b32_e32 v106, v2
	v_mov_b32_e32 v107, v2
	v_mov_b32_e32 v108, v2
	v_mov_b32_e32 v109, v2
	v_mov_b32_e32 v114, v2
	v_mov_b32_e32 v115, v2
	v_mov_b32_e32 v116, v2
	v_mov_b32_e32 v117, v2
	v_mov_b32_e32 v122, v2
	v_mov_b32_e32 v123, v2
	v_mov_b32_e32 v124, v2
	v_mov_b32_e32 v125, v2
	v_mov_b32_e32 v70, v2
	v_mov_b32_e32 v71, v2
	v_mov_b32_e32 v72, v2
	v_mov_b32_e32 v73, v2
	v_mov_b32_e32 v78, v2
	v_mov_b32_e32 v79, v2
	v_mov_b32_e32 v80, v2
	v_mov_b32_e32 v81, v2
	v_mov_b32_e32 v86, v2
	v_mov_b32_e32 v87, v2
	v_mov_b32_e32 v88, v2
	v_mov_b32_e32 v89, v2
	v_mov_b32_e32 v94, v2
	v_mov_b32_e32 v95, v2
	v_mov_b32_e32 v96, v2
	v_mov_b32_e32 v97, v2
	v_mov_b32_e32 v102, v2
	v_mov_b32_e32 v103, v2
	v_mov_b32_e32 v104, v2
	v_mov_b32_e32 v105, v2
	v_mov_b32_e32 v110, v2
	v_mov_b32_e32 v111, v2
	v_mov_b32_e32 v112, v2
	v_mov_b32_e32 v113, v2
	v_mov_b32_e32 v118, v2
	v_mov_b32_e32 v119, v2
	v_mov_b32_e32 v120, v2
	v_mov_b32_e32 v121, v2
	v_mov_b32_e32 v126, v2
	v_mov_b32_e32 v127, v2
	v_mov_b32_e32 v128, v2
	v_mov_b32_e32 v129, v2
	s_branch .Lpeel124_125
.Lpeel124_125:
	s_cmp_lg_u32 s69, s4
	s_cselect_b64 s[52:53], -1, 0
	s_cmp_eq_u32 s69, s4
	s_mov_b64 s[2:3], s[42:43]
	s_cbranch_scc1 .Lpeel124_127
	s_add_u32 s2, s6, s92
	s_addc_u32 s3, s7, s93

; #define PG8_STAGE(bufoff, gbase, voff) do { _Pragma("unroll") for (int _i = 0; _i < 2; ++_i) \
;         __builtin_amdgcn_global_load_lds((const unsigned*)((const char*)(gbase) + (voff)[_i]), (LAS unsigned*)(lds + (bufoff) + ldsw + _i * 8192), 16, 0, 0); } while (0)
; #define PG8_LDA(dst, b, h) do { _Pragma("unroll") for (int m = 0; m < 4; ++m) _Pragma("unroll") for (int k = 0; k < 2; ++k) dst[m][k] = *(const LAS bf16x8*)(lds + PG8_SA(b, h) + aoff + m * 2048 + k * 1024); } while (0)
; #define PG8_LDB(dst, b, h) do { _Pragma("unroll") for (int n = 0; n < 2; ++n) _Pragma("unroll") for (int k = 0; k < 2; ++k) dst[n][k] = *(const LAS bf16x8*)(lds + PG8_SB(b, h) + boff + n * 2048 + k * 1024); } while (0)
; #define PG8_MMA(ai, bj, At, Bt) do { __builtin_amdgcn_s_setprio(1); _Pragma("unroll") for (int m = 0; m < 4; ++m) _Pragma("unroll") for (int n = 0; n < 2; ++n) _Pragma("unroll") for (int k = 0; k < 2; ++k) \
;         acc[ai][bj][m][n] = __builtin_amdgcn_mfma_f32_16x16x32_bf16(Bt[n][k], At[m][k], acc[ai][bj][m][n], 0, 0, 0); __builtin_amdgcn_s_setprio(0); } while (0)
; #define PG8_WAIT_V(n) asm volatile("s_waitcnt vmcnt(" #n ")" ::: "memory")
; #define PG8_WAIT_L(n) asm volatile("s_waitcnt lgkmcnt(" #n ")" ::: "memory")
; #define PG8_BAR __builtin_amdgcn_s_barrier()
; #define PG8_SCHED __builtin_amdgcn_sched_barrier(0)
; template <int MODE> __device__ __forceinline__ void gemm_phase(LAS unsigned char* lds, const GD& g, const int tid) {
;     ...
;         for (int t = 0; t < nt; t += 2) {
;             const bool last = (t == nt - 2);
;             const char* a1 = cA + (size_t)(t + 1) * kstA;
;             const char* a2 = last ? nA : cA + (size_t)(t + 2) * kstA; const char* b2 = last ? nB : cB + (size_t)(t + 2) * kstB;
;             const char* a3 = a2 + kstA; const char* b3 = b2 + kstB;
;             PG8_LDB(B0, 0, 0); PG8_LDB(B1, 0, 1); PG8_SCHED; PG8_LDA(At, 0, 0); PG8_STAGE(PG8_SA(1, 1), a1 + hsA, voffA);
;             PG8_WAIT_V(8); PG8_WAIT_L(0); PG8_BAR; PG8_MMA(0, 0, At, B0); PG8_MMA(0, 1, At, B1); PG8_BAR; PG8_SCHED;
;             PG8_LDA(At, 0, 1); PG8_STAGE(PG8_SB(0, 0), b2, voffB); PG8_STAGE(PG8_SB(0, 1), b2 + hsB, voffB); PG8_STAGE(PG8_SA(0, 0), a2, voffA);
;             PG8_WAIT_V(8); PG8_WAIT_L(0); PG8_BAR; PG8_MMA(1, 0, At, B0); PG8_MMA(1, 1, At, B1); PG8_BAR; PG8_SCHED;
.Lpeel124_124:
	s_add_i32 s4, s4, 2
	s_add_u32 s64, s2, s20
	s_addc_u32 s65, s3, s21
	s_add_i32 s5, 0, 0x10000
	v_add_u32_e32 v1, s5, v153
	s_add_i32 s12, 0, 0x14000
	ds_read_b128 v[158:161], v1
	ds_read_b128 v[162:165], v1 offset:1024
	ds_read_b128 v[166:169], v1 offset:2048
	ds_read_b128 v[170:173], v1 offset:3072
	v_add_u32_e32 v1, s12, v153
	ds_read_b128 v[174:177], v1
	ds_read_b128 v[178:181], v1 offset:1024
	ds_read_b128 v[182:185], v1 offset:2048
	ds_read_b128 v[186:189], v1 offset:3072
	v_lshl_add_u64 v[142:143], s[6:7], 0, v[140:141]
	s_add_i32 m0, s27, 0xc000
	ds_read_b128 v[190:193], v156
	ds_read_b128 v[196:199], v156 offset:1024
	ds_read_b128 v[204:207], v156 offset:2048
	ds_read_b128 v[220:223], v156 offset:3072
	ds_read_b128 v[224:227], v156 offset:4096
	ds_read_b128 v[228:231], v156 offset:5120
	ds_read_b128 v[232:235], v156 offset:6144
	ds_read_b128 v[236:239], v156 offset:7168
	global_load_lds_dwordx4 v[142:143], off
	v_lshl_add_u64 v[142:143], s[6:7], 0, v[138:139]
	s_add_i32 m0, s27, 0xe000
	s_nop 0
	global_load_lds_dwordx4 v[142:143], off
	s_waitcnt vmcnt(24)
	s_waitcnt lgkmcnt(0)
	s_barrier
	s_setprio 1
	s_waitcnt lgkmcnt(0)
	v_mfma_f32_16x16x32_bf16 v[126:129], v[158:161], v[190:193], v[126:129]
	v_mfma_f32_16x16x32_bf16 v[118:121], v[166:169], v[190:193], v[118:121]
	v_mfma_f32_16x16x32_bf16 v[110:113], v[158:161], v[204:207], v[110:113]
	v_mfma_f32_16x16x32_bf16 v[102:105], v[166:169], v[204:207], v[102:105]
	v_mfma_f32_16x16x32_bf16 v[94:97], v[158:161], v[224:227], v[94:97]
	v_mfma_f32_16x16x32_bf16 v[86:89], v[166:169], v[224:227], v[86:89]
	v_mfma_f32_16x16x32_bf16 v[78:81], v[158:161], v[232:235], v[78:81]
	v_mfma_f32_16x16x32_bf16 v[70:73], v[166:169], v[232:235], v[70:73]
	v_mfma_f32_16x16x32_bf16 v[126:129], v[162:165], v[196:199], v[126:129]
	v_mfma_f32_16x16x32_bf16 v[118:121], v[170:173], v[196:199], v[118:121]
	v_mfma_f32_16x16x32_bf16 v[110:113], v[162:165], v[220:223], v[110:113]
	v_mfma_f32_16x16x32_bf16 v[102:105], v[170:173], v[220:223], v[102:105]
	v_mfma_f32_16x16x32_bf16 v[94:97], v[162:165], v[228:231], v[94:97]
	v_mfma_f32_16x16x32_bf16 v[86:89], v[170:173], v[228:231], v[86:89]
	v_mfma_f32_16x16x32_bf16 v[78:81], v[162:165], v[236:239], v[78:81]
	v_mfma_f32_16x16x32_bf16 v[70:73], v[170:173], v[236:239], v[70:73]
	s_setprio 0
	s_setprio 1
	v_mfma_f32_16x16x32_bf16 v[122:125], v[174:177], v[190:193], v[122:125]
	v_mfma_f32_16x16x32_bf16 v[114:117], v[182:185], v[190:193], v[114:117]
	v_mfma_f32_16x16x32_bf16 v[106:109], v[174:177], v[204:207], v[106:109]
	v_mfma_f32_16x16x32_bf16 v[98:101], v[182:185], v[204:207], v[98:101]
	v_mfma_f32_16x16x32_bf16 v[90:93], v[174:177], v[224:227], v[90:93]
	v_mfma_f32_16x16x32_bf16 v[82:85], v[182:185], v[224:227], v[82:85]
	v_mfma_f32_16x16x32_bf16 v[74:77], v[174:177], v[232:235], v[74:77]
	v_mfma_f32_16x16x32_bf16 v[66:69], v[182:185], v[232:235], v[66:69]
	v_mfma_f32_16x16x32_bf16 v[122:125], v[178:181], v[196:199], v[122:125]
	v_mfma_f32_16x16x32_bf16 v[114:117], v[186:189], v[196:199], v[114:117]
	v_mfma_f32_16x16x32_bf16 v[106:109], v[178:181], v[220:223], v[106:109]
	v_mfma_f32_16x16x32_bf16 v[98:101], v[186:189], v[220:223], v[98:101]
	v_mfma_f32_16x16x32_bf16 v[90:93], v[178:181], v[228:231], v[90:93]
	v_mfma_f32_16x16x32_bf16 v[82:85], v[186:189], v[228:231], v[82:85]
	v_mfma_f32_16x16x32_bf16 v[74:77], v[178:181], v[236:239], v[74:77]
	v_mfma_f32_16x16x32_bf16 v[66:69], v[186:189], v[236:239], v[66:69]
	s_setprio 0
	s_barrier
	s_add_i32 s5, s5, s25
	v_lshl_add_u64 v[142:143], s[52:53], 0, v[132:133]
	s_mov_b32 m0, s5
	ds_read_b128 v[190:193], v156 offset:16384
	ds_read_b128 v[196:199], v156 offset:17408
	ds_read_b128 v[204:207], v156 offset:18432
	ds_read_b128 v[220:223], v156 offset:19456
	ds_read_b128 v[224:227], v156 offset:20480
	ds_read_b128 v[228:231], v156 offset:21504
	ds_read_b128 v[232:235], v156 offset:22528
	ds_read_b128 v[236:239], v156 offset:23552
	global_load_lds_dwordx4 v[142:143], off
	s_add_i32 m0, s5, 0x2000
	s_add_u32 s10, s52, s46
	v_lshl_add_u64 v[142:143], s[52:53], 0, v[136:137]
	s_addc_u32 s11, s53, s47
	s_add_i32 s5, s12, s25
	global_load_lds_dwordx4 v[142:143], off
	v_lshl_add_u64 v[142:143], s[10:11], 0, v[132:133]
	s_mov_b32 m0, s5
	s_nop 0
	global_load_lds_dwordx4 v[142:143], off
	v_lshl_add_u64 v[142:143], s[10:11], 0, v[136:137]
	s_add_i32 m0, s5, 0x2000
	s_nop 0
	global_load_lds_dwordx4 v[142:143], off
	v_lshl_add_u64 v[142:143], s[2:3], 0, v[130:131]
	s_mov_b32 m0, s27
	s_nop 0
	global_load_lds_dwordx4 v[142:143], off
	v_lshl_add_u64 v[142:143], s[2:3], 0, v[134:135]
	s_mov_b32 m0, s74
	s_nop 0
	global_load_lds_dwordx4 v[142:143], off
	s_waitcnt vmcnt(24)
	s_waitcnt lgkmcnt(0)
	s_barrier
; #define PG8_STAGE(bufoff, gbase, voff) do { _Pragma("unroll") for (int _i = 0; _i < 2; ++_i) \
;         __builtin_amdgcn_global_load_lds((const unsigned*)((const char*)(gbase) + (voff)[_i]), (LAS unsigned*)(lds + (bufoff) + ldsw + _i * 8192), 16, 0, 0); } while (0)
; #define PG8_LDA(dst, b, h) do { _Pragma("unroll") for (int m = 0; m < 4; ++m) _Pragma("unroll") for (int k = 0; k < 2; ++k) dst[m][k] = *(const LAS bf16x8*)(lds + PG8_SA(b, h) + aoff + m * 2048 + k * 1024); } while (0)
; #define PG8_LDB(dst, b, h) do { _Pragma("unroll") for (int n = 0; n < 2; ++n) _Pragma("unroll") for (int k = 0; k < 2; ++k) dst[n][k] = *(const LAS bf16x8*)(lds + PG8_SB(b, h) + boff + n * 2048 + k * 1024); } while (0)
; #define PG8_MMA(ai, bj, At, Bt) do { __builtin_amdgcn_s_setprio(1); _Pragma("unroll") for (int m = 0; m < 4; ++m) _Pragma("unroll") for (int n = 0; n < 2; ++n) _Pragma("unroll") for (int k = 0; k < 2; ++k) \
;         acc[ai][bj][m][n] = __builtin_amdgcn_mfma_f32_16x16x32_bf16(Bt[n][k], At[m][k], acc[ai][bj][m][n], 0, 0, 0); __builtin_amdgcn_s_setprio(0); } while (0)
; #define PG8_WAIT_V(n) asm volatile("s_waitcnt vmcnt(" #n ")" ::: "memory")
; #define PG8_WAIT_L(n) asm volatile("s_waitcnt lgkmcnt(" #n ")" ::: "memory")
; #define PG8_BAR __builtin_amdgcn_s_barrier()
; #define PG8_SCHED __builtin_amdgcn_sched_barrier(0)
; template <int MODE> __device__ __forceinline__ void gemm_phase(LAS unsigned char* lds, const GD& g, const int tid) {
;     ...
;             PG8_WAIT_V(8); PG8_WAIT_L(0); PG8_BAR; PG8_MMA(1, 0, At, B0); PG8_MMA(1, 1, At, B1); PG8_BAR; PG8_SCHED;
;             PG8_LDB(B0, 1, 0); PG8_LDB(B1, 1, 1); PG8_SCHED; PG8_LDA(At, 1, 0); PG8_STAGE(PG8_SA(0, 1), a2 + hsA, voffA);
;             PG8_WAIT_V(8); PG8_WAIT_L(0); PG8_BAR; PG8_MMA(0, 0, At, B0); PG8_MMA(0, 1, At, B1); PG8_BAR; PG8_SCHED;
	s_setprio 1
	s_waitcnt lgkmcnt(0)
	v_mfma_f32_16x16x32_bf16 v[62:65], v[158:161], v[190:193], v[62:65]
	v_mfma_f32_16x16x32_bf16 v[54:57], v[166:169], v[190:193], v[54:57]
	v_mfma_f32_16x16x32_bf16 v[46:49], v[158:161], v[204:207], v[46:49]
	v_mfma_f32_16x16x32_bf16 v[38:41], v[166:169], v[204:207], v[38:41]
	v_mfma_f32_16x16x32_bf16 v[30:33], v[158:161], v[224:227], v[30:33]
	v_mfma_f32_16x16x32_bf16 v[22:25], v[166:169], v[224:227], v[22:25]
	v_mfma_f32_16x16x32_bf16 v[14:17], v[158:161], v[232:235], v[14:17]
	v_mfma_f32_16x16x32_bf16 v[6:9], v[166:169], v[232:235], v[6:9]
	v_mfma_f32_16x16x32_bf16 v[62:65], v[162:165], v[196:199], v[62:65]
	v_mfma_f32_16x16x32_bf16 v[54:57], v[170:173], v[196:199], v[54:57]
	v_mfma_f32_16x16x32_bf16 v[46:49], v[162:165], v[220:223], v[46:49]
	v_mfma_f32_16x16x32_bf16 v[38:41], v[170:173], v[220:223], v[38:41]
	v_mfma_f32_16x16x32_bf16 v[30:33], v[162:165], v[228:231], v[30:33]
	v_mfma_f32_16x16x32_bf16 v[22:25], v[170:173], v[228:231], v[22:25]
	v_mfma_f32_16x16x32_bf16 v[14:17], v[162:165], v[236:239], v[14:17]
	v_mfma_f32_16x16x32_bf16 v[6:9], v[170:173], v[236:239], v[6:9]
	s_setprio 0
	s_setprio 1
	v_mfma_f32_16x16x32_bf16 v[58:61], v[174:177], v[190:193], v[58:61]
	v_mfma_f32_16x16x32_bf16 v[50:53], v[182:185], v[190:193], v[50:53]
	v_mfma_f32_16x16x32_bf16 v[42:45], v[174:177], v[204:207], v[42:45]
	v_mfma_f32_16x16x32_bf16 v[34:37], v[182:185], v[204:207], v[34:37]
	v_mfma_f32_16x16x32_bf16 v[26:29], v[174:177], v[224:227], v[26:29]
	v_mfma_f32_16x16x32_bf16 v[18:21], v[182:185], v[224:227], v[18:21]
	v_mfma_f32_16x16x32_bf16 v[10:13], v[174:177], v[232:235], v[10:13]
	v_mfma_f32_16x16x32_bf16 v[2:5], v[182:185], v[232:235], v[2:5]
	v_mfma_f32_16x16x32_bf16 v[58:61], v[178:181], v[196:199], v[58:61]
	v_mfma_f32_16x16x32_bf16 v[50:53], v[186:189], v[196:199], v[50:53]
	v_mfma_f32_16x16x32_bf16 v[42:45], v[178:181], v[220:223], v[42:45]
	v_mfma_f32_16x16x32_bf16 v[34:37], v[186:189], v[220:223], v[34:37]
	v_mfma_f32_16x16x32_bf16 v[26:29], v[178:181], v[228:231], v[26:29]
	v_mfma_f32_16x16x32_bf16 v[18:21], v[186:189], v[228:231], v[18:21]
	v_mfma_f32_16x16x32_bf16 v[10:13], v[178:181], v[236:239], v[10:13]
	v_mfma_f32_16x16x32_bf16 v[2:5], v[186:189], v[236:239], v[2:5]
	s_setprio 0
	s_barrier
	s_add_i32 s5, 0, 0x18000
	v_add_u32_e32 v1, s5, v153
	s_add_i32 s10, 0, 0x1c000
	ds_read_b128 v[158:161], v1
	ds_read_b128 v[162:165], v1 offset:1024
	ds_read_b128 v[166:169], v1 offset:2048
	ds_read_b128 v[170:173], v1 offset:3072
	v_add_u32_e32 v1, s10, v153
	ds_read_b128 v[174:177], v1
	ds_read_b128 v[178:181], v1 offset:1024
	ds_read_b128 v[182:185], v1 offset:2048
	ds_read_b128 v[186:189], v1 offset:3072
	s_add_u32 s2, s2, s44
	s_addc_u32 s3, s3, s45
	s_mov_b32 m0, s75
	v_lshl_add_u64 v[142:143], s[2:3], 0, v[130:131]
	ds_read_b128 v[190:193], v156 offset:32768
	ds_read_b128 v[196:199], v156 offset:33792
	ds_read_b128 v[204:207], v156 offset:34816
	ds_read_b128 v[220:223], v156 offset:35840
	ds_read_b128 v[224:227], v156 offset:36864
	ds_read_b128 v[228:231], v156 offset:37888
	ds_read_b128 v[232:235], v156 offset:38912
	ds_read_b128 v[236:239], v156 offset:39936
	global_load_lds_dwordx4 v[142:143], off
	v_lshl_add_u64 v[142:143], s[2:3], 0, v[134:135]
	s_mov_b32 m0, s68
	s_nop 0
	global_load_lds_dwordx4 v[142:143], off
	s_waitcnt vmcnt(8)
	s_waitcnt lgkmcnt(0)
	s_barrier
	s_setprio 1
	s_waitcnt lgkmcnt(0)
	v_mfma_f32_16x16x32_bf16 v[126:129], v[158:161], v[190:193], v[126:129]
	v_mfma_f32_16x16x32_bf16 v[118:121], v[166:169], v[190:193], v[118:121]
	v_mfma_f32_16x16x32_bf16 v[110:113], v[158:161], v[204:207], v[110:113]
	v_mfma_f32_16x16x32_bf16 v[102:105], v[166:169], v[204:207], v[102:105]
	v_mfma_f32_16x16x32_bf16 v[94:97], v[158:161], v[224:227], v[94:97]
	v_mfma_f32_16x16x32_bf16 v[86:89], v[166:169], v[224:227], v[86:89]
	v_mfma_f32_16x16x32_bf16 v[78:81], v[158:161], v[232:235], v[78:81]
	v_mfma_f32_16x16x32_bf16 v[70:73], v[166:169], v[232:235], v[70:73]
	v_mfma_f32_16x16x32_bf16 v[126:129], v[162:165], v[196:199], v[126:129]
	v_mfma_f32_16x16x32_bf16 v[118:121], v[170:173], v[196:199], v[118:121]
	v_mfma_f32_16x16x32_bf16 v[110:113], v[162:165], v[220:223], v[110:113]
	v_mfma_f32_16x16x32_bf16 v[102:105], v[170:173], v[220:223], v[102:105]
	v_mfma_f32_16x16x32_bf16 v[94:97], v[162:165], v[228:231], v[94:97]
	v_mfma_f32_16x16x32_bf16 v[86:89], v[170:173], v[228:231], v[86:89]
	v_mfma_f32_16x16x32_bf16 v[78:81], v[162:165], v[236:239], v[78:81]
	v_mfma_f32_16x16x32_bf16 v[70:73], v[170:173], v[236:239], v[70:73]
	s_setprio 0
	s_setprio 1
	v_mfma_f32_16x16x32_bf16 v[122:125], v[174:177], v[190:193], v[122:125]
	v_mfma_f32_16x16x32_bf16 v[114:117], v[182:185], v[190:193], v[114:117]
	v_mfma_f32_16x16x32_bf16 v[106:109], v[174:177], v[204:207], v[106:109]
	v_mfma_f32_16x16x32_bf16 v[98:101], v[182:185], v[204:207], v[98:101]
	v_mfma_f32_16x16x32_bf16 v[90:93], v[174:177], v[224:227], v[90:93]
	v_mfma_f32_16x16x32_bf16 v[82:85], v[182:185], v[224:227], v[82:85]
	v_mfma_f32_16x16x32_bf16 v[74:77], v[174:177], v[232:235], v[74:77]
	v_mfma_f32_16x16x32_bf16 v[66:69], v[182:185], v[232:235], v[66:69]
	v_mfma_f32_16x16x32_bf16 v[122:125], v[178:181], v[196:199], v[122:125]
	v_mfma_f32_16x16x32_bf16 v[114:117], v[186:189], v[196:199], v[114:117]
	v_mfma_f32_16x16x32_bf16 v[106:109], v[178:181], v[220:223], v[106:109]
	v_mfma_f32_16x16x32_bf16 v[98:101], v[186:189], v[220:223], v[98:101]
	v_mfma_f32_16x16x32_bf16 v[90:93], v[178:181], v[228:231], v[90:93]
	v_mfma_f32_16x16x32_bf16 v[82:85], v[186:189], v[228:231], v[82:85]
	v_mfma_f32_16x16x32_bf16 v[74:77], v[178:181], v[236:239], v[74:77]
	v_mfma_f32_16x16x32_bf16 v[66:69], v[186:189], v[236:239], v[66:69]
	s_setprio 0
	s_barrier
; #define PG8_STAGE(bufoff, gbase, voff) do { _Pragma("unroll") for (int _i = 0; _i < 2; ++_i) \
;         __builtin_amdgcn_global_load_lds((const unsigned*)((const char*)(gbase) + (voff)[_i]), (LAS unsigned*)(lds + (bufoff) + ldsw + _i * 8192), 16, 0, 0); } while (0)
; #define PG8_LDA(dst, b, h) do { _Pragma("unroll") for (int m = 0; m < 4; ++m) _Pragma("unroll") for (int k = 0; k < 2; ++k) dst[m][k] = *(const LAS bf16x8*)(lds + PG8_SA(b, h) + aoff + m * 2048 + k * 1024); } while (0)
; #define PG8_MMA(ai, bj, At, Bt) do { __builtin_amdgcn_s_setprio(1); _Pragma("unroll") for (int m = 0; m < 4; ++m) _Pragma("unroll") for (int n = 0; n < 2; ++n) _Pragma("unroll") for (int k = 0; k < 2; ++k) \
;         acc[ai][bj][m][n] = __builtin_amdgcn_mfma_f32_16x16x32_bf16(Bt[n][k], At[m][k], acc[ai][bj][m][n], 0, 0, 0); __builtin_amdgcn_s_setprio(0); } while (0)
; #define PG8_WAIT_V(n) asm volatile("s_waitcnt vmcnt(" #n ")" ::: "memory")
; #define PG8_WAIT_L(n) asm volatile("s_waitcnt lgkmcnt(" #n ")" ::: "memory")
; #define PG8_BAR __builtin_amdgcn_s_barrier()
; #define PG8_SCHED __builtin_amdgcn_sched_barrier(0)
; template <int MODE> __device__ __forceinline__ void gemm_phase(LAS unsigned char* lds, const GD& g, const int tid) {
;     ...
;             PG8_LDA(At, 1, 1); PG8_STAGE(PG8_SB(1, 0), b3, voffB); PG8_STAGE(PG8_SB(1, 1), b3 + hsB, voffB); PG8_STAGE(PG8_SA(1, 0), a3, voffA);
;             PG8_WAIT_V(8); PG8_WAIT_L(0); PG8_BAR; PG8_MMA(1, 0, At, B0); PG8_MMA(1, 1, At, B1); PG8_BAR; PG8_SCHED;
;         }
	s_add_u32 s2, s52, s22
	s_addc_u32 s3, s53, s23
	s_add_i32 s5, s5, s25
	v_lshl_add_u64 v[142:143], s[2:3], 0, v[132:133]
	s_mov_b32 m0, s5
	ds_read_b128 v[190:193], v156 offset:49152
	ds_read_b128 v[196:199], v156 offset:50176
	ds_read_b128 v[204:207], v156 offset:51200
	ds_read_b128 v[220:223], v156 offset:52224
	ds_read_b128 v[224:227], v156 offset:53248
	ds_read_b128 v[228:231], v156 offset:54272
	ds_read_b128 v[232:235], v156 offset:55296
	ds_read_b128 v[236:239], v156 offset:56320
	global_load_lds_dwordx4 v[142:143], off
	s_add_i32 m0, s5, 0x2000
	v_lshl_add_u64 v[142:143], s[2:3], 0, v[136:137]
	s_add_u32 s2, s2, s46
	s_addc_u32 s3, s3, s47
	s_add_i32 s5, s10, s25
	global_load_lds_dwordx4 v[142:143], off
	v_lshl_add_u64 v[142:143], s[2:3], 0, v[132:133]
	s_mov_b32 m0, s5
	s_nop 0
	global_load_lds_dwordx4 v[142:143], off
	v_lshl_add_u64 v[142:143], s[2:3], 0, v[136:137]
	s_add_i32 m0, s5, 0x2000
	s_nop 0
	global_load_lds_dwordx4 v[142:143], off
	v_lshl_add_u64 v[142:143], s[64:65], 0, v[130:131]
	s_mov_b32 m0, s58
	s_nop 0
	global_load_lds_dwordx4 v[142:143], off
	v_lshl_add_u64 v[142:143], s[64:65], 0, v[134:135]
	s_mov_b32 m0, s59
	s_nop 0
	global_load_lds_dwordx4 v[142:143], off
	s_waitcnt vmcnt(8)
	s_waitcnt lgkmcnt(0)
	s_barrier
	s_setprio 1
	s_waitcnt lgkmcnt(0)
	v_mfma_f32_16x16x32_bf16 v[62:65], v[158:161], v[190:193], v[62:65]
	v_mfma_f32_16x16x32_bf16 v[54:57], v[166:169], v[190:193], v[54:57]
	v_mfma_f32_16x16x32_bf16 v[46:49], v[158:161], v[204:207], v[46:49]
	v_mfma_f32_16x16x32_bf16 v[38:41], v[166:169], v[204:207], v[38:41]
	v_mfma_f32_16x16x32_bf16 v[30:33], v[158:161], v[224:227], v[30:33]
	v_mfma_f32_16x16x32_bf16 v[22:25], v[166:169], v[224:227], v[22:25]
	v_mfma_f32_16x16x32_bf16 v[14:17], v[158:161], v[232:235], v[14:17]
	v_mfma_f32_16x16x32_bf16 v[6:9], v[166:169], v[232:235], v[6:9]
	v_mfma_f32_16x16x32_bf16 v[62:65], v[162:165], v[196:199], v[62:65]
	v_mfma_f32_16x16x32_bf16 v[54:57], v[170:173], v[196:199], v[54:57]
	v_mfma_f32_16x16x32_bf16 v[46:49], v[162:165], v[220:223], v[46:49]
	v_mfma_f32_16x16x32_bf16 v[38:41], v[170:173], v[220:223], v[38:41]
	v_mfma_f32_16x16x32_bf16 v[30:33], v[162:165], v[228:231], v[30:33]
	v_mfma_f32_16x16x32_bf16 v[22:25], v[170:173], v[228:231], v[22:25]
	v_mfma_f32_16x16x32_bf16 v[14:17], v[162:165], v[236:239], v[14:17]
	v_mfma_f32_16x16x32_bf16 v[6:9], v[170:173], v[236:239], v[6:9]
	s_setprio 0
	s_setprio 1
	v_mfma_f32_16x16x32_bf16 v[58:61], v[174:177], v[190:193], v[58:61]
	v_mfma_f32_16x16x32_bf16 v[50:53], v[182:185], v[190:193], v[50:53]
	v_mfma_f32_16x16x32_bf16 v[42:45], v[174:177], v[204:207], v[42:45]
	v_mfma_f32_16x16x32_bf16 v[34:37], v[182:185], v[204:207], v[34:37]
	v_mfma_f32_16x16x32_bf16 v[26:29], v[174:177], v[224:227], v[26:29]
	v_mfma_f32_16x16x32_bf16 v[18:21], v[182:185], v[224:227], v[18:21]
	v_mfma_f32_16x16x32_bf16 v[10:13], v[174:177], v[232:235], v[10:13]
	v_mfma_f32_16x16x32_bf16 v[2:5], v[182:185], v[232:235], v[2:5]
	v_mfma_f32_16x16x32_bf16 v[58:61], v[178:181], v[196:199], v[58:61]
	v_mfma_f32_16x16x32_bf16 v[50:53], v[186:189], v[196:199], v[50:53]
	v_mfma_f32_16x16x32_bf16 v[42:45], v[178:181], v[220:223], v[42:45]
	v_mfma_f32_16x16x32_bf16 v[34:37], v[186:189], v[220:223], v[34:37]
	v_mfma_f32_16x16x32_bf16 v[26:29], v[178:181], v[228:231], v[26:29]
	v_mfma_f32_16x16x32_bf16 v[18:21], v[186:189], v[228:231], v[18:21]
	v_mfma_f32_16x16x32_bf16 v[10:13], v[178:181], v[236:239], v[10:13]
	v_mfma_f32_16x16x32_bf16 v[2:5], v[186:189], v[236:239], v[2:5]
	s_setprio 0
	s_barrier
	s_add_u32 s50, s50, s86
	s_addc_u32 s51, s51, s87
	s_add_u32 s6, s6, s92
	s_addc_u32 s7, s7, s93
	s_cmp_ge_i32 s4, s17
	s_cbranch_scc1 .LBB0_130
	s_branch .LBB0_125

; #define PG8_STAGE(bufoff, gbase, voff) do { _Pragma("unroll") for (int _i = 0; _i < 2; ++_i) \
;         __builtin_amdgcn_global_load_lds((const unsigned*)((const char*)(gbase) + (voff)[_i]), (LAS unsigned*)(lds + (bufoff) + ldsw + _i * 8192), 16, 0, 0); } while (0)
; #define PG8_WAIT_V(n) asm volatile("s_waitcnt vmcnt(" #n ")" ::: "memory")
; #define PG8_BAR __builtin_amdgcn_s_barrier()
; template <int MODE> __device__ __forceinline__ void gemm_phase(LAS unsigned char* lds, const GD& g, const int tid) {
;     ...
;     PG8_STAGE(PG8_SB(0, 0), cB, voffB); PG8_STAGE(PG8_SB(0, 1), cB + hsB, voffB); PG8_STAGE(PG8_SA(0, 0), cA, voffA); PG8_STAGE(PG8_SA(0, 1), cA + hsA, voffA);
;     if (wr == 1) PG8_BAR;
;     PG8_WAIT_V(2); PG8_BAR;
;     PG8_STAGE(PG8_SB(1, 0), cB + kstB, voffB); PG8_STAGE(PG8_SA(1, 0), cA + kstA, voffA); PG8_STAGE(PG8_SB(1, 1), cB + hsB + kstB, voffB);
;     PG8_WAIT_V(6); PG8_BAR;
;     for (;;) {
;         const bool has_next = gd_next(g, ui + 1, nxt);
.LBB0_166:
	v_readlane_b32 s6, v254, 62
	s_ashr_i32 s4, s6, 31
	s_lshr_b32 s4, s4, 26
	v_bfe_u32 v10, v194, 4, 2
	s_add_i32 s4, s6, s4
	s_ashr_i32 s30, s4, 6
	v_lshlrev_b32_e32 v8, 4, v10
	v_lshlrev_b32_e32 v9, 6, v154
	s_movk_i32 s4, 0x3c0
	v_lshlrev_b32_e32 v11, 2, v154
	v_and_or_b32 v9, v9, s4, v8
	s_lshl_b32 s0, s0, 13
	v_and_b32_e32 v11, 32, v11
	v_bitop3_b32 v11, v9, s0, v11 bitop3:0xde
	s_lshl_b32 s0, s1, 5
	s_and_b32 s12, s0, 0x60
	v_lshl_or_b32 v8, v7, 6, v8
	v_lshlrev_b32_e32 v7, 2, v7
	s_ashr_i32 s21, s20, 31
	s_ashr_i32 s23, s22, 31
	s_lshl_b32 s0, s12, 7
	v_and_b32_e32 v7, 32, v7
	v_bitop3_b32 v163, s0, v8, v7 bitop3:0xf6
	s_add_u32 s0, s68, s22
	v_mov_b32_e32 v133, v0
	s_addc_u32 s1, s69, s23
	s_add_i32 m0, s17, 0x18000
	v_lshl_add_u64 v[8:9], s[0:1], 0, v[132:133]
	v_mov_b32_e32 v137, v0
	s_waitcnt vmcnt(2)
	s_barrier
	global_load_lds_dwordx4 v[8:9], off
	s_add_i32 m0, s17, 0x1a000
	v_lshl_add_u64 v[8:9], s[0:1], 0, v[136:137]
	s_add_u32 s0, s8, s20
	v_mov_b32_e32 v131, v0
	s_addc_u32 s1, s9, s21
	s_add_i32 s28, s17, 0x8000
	v_mov_b32_e32 v135, v0
	global_load_lds_dwordx4 v[8:9], off
	v_lshl_add_u64 v[8:9], s[0:1], 0, v[130:131]
	s_mov_b32 m0, s28
	s_add_i32 s29, s17, 0xa000
	global_load_lds_dwordx4 v[8:9], off
	v_lshl_add_u64 v[8:9], s[0:1], 0, v[134:135]
	s_add_u32 s0, s2, s22
	s_mov_b32 m0, s29
	s_addc_u32 s1, s3, s23
	global_load_lds_dwordx4 v[8:9], off
	s_add_i32 m0, s17, 0x1c000
	v_lshl_add_u64 v[8:9], s[0:1], 0, v[132:133]
	global_load_lds_dwordx4 v[8:9], off
	s_add_i32 m0, s17, 0x1e000
	s_cmp_gt_i32 s6, 63
	v_lshl_add_u64 v[8:9], s[0:1], 0, v[136:137]
	s_cselect_b64 s[50:51], -1, 0
	s_add_i32 s27, s30, -2
	v_readlane_b32 s13, v254, 33
	v_readlane_b32 s0, v254, 60
	s_mul_i32 s14, s59, s13
	s_cmp_lg_u32 s0, 1
	s_mul_i32 s4, s0, s14
	s_cselect_b64 s[0:1], -1, 0
	v_writelane_b32 v255, s0, 2
	s_cmp_eq_u32 s13, 16
	v_lshl_or_b32 v164, v10, 2, s12
	v_writelane_b32 v255, s1, 3
	s_cselect_b64 s[0:1], -1, 0
	s_and_b32 s2, s59, 3
	s_cmp_eq_u32 s2, 0
	s_cselect_b64 s[2:3], -1, 0
	s_and_b64 s[0:1], s[0:1], s[2:3]
	s_and_b32 s2, s5, 7
	s_cmp_eq_u32 s2, 0
	s_cselect_b64 s[2:3], -1, 0
	s_and_b64 s[0:1], s[0:1], s[2:3]
	v_writelane_b32 v255, s0, 16
	s_lshl_b32 s15, s59, 3
	global_load_lds_dwordx4 v[8:9], off
	v_writelane_b32 v255, s1, 17
	s_xor_b64 s[0:1], s[0:1], -1
	v_writelane_b32 v255, s0, 20
	s_waitcnt vmcnt(0)
	v_add_u32_e32 v4, v6, v4
	v_add_u32_e32 v1, v3, v1
	v_writelane_b32 v255, s1, 21
	s_and_b32 s0, s10, 7
	s_ashr_i32 s1, s5, 3
	s_mul_i32 s0, s1, s0
	s_lshr_b32 s1, s10, 3
	s_add_i32 s0, s0, s1
	v_writelane_b32 v255, s0, 27
	s_ashr_i32 s0, s14, 31
	v_writelane_b32 v255, s0, 4
	s_lshr_b32 s0, s0, 29
	s_add_i32 s0, s14, s0
	s_ashr_i32 s1, s0, 3
	s_and_b32 s0, s0, -8
	s_sub_i32 s35, s14, s0
	s_add_i32 s0, s1, 1
	s_cmp_lg_u64 s[36:37], 0
	s_cselect_b64 s[62:63], -1, 0
	s_abs_i32 s2, s5
	v_cvt_f32_u32_e32 v7, s2
	s_sub_i32 s3, 0, s2
	v_writelane_b32 v255, s1, 30
	s_abs_i32 s1, s4
	v_rcp_iflag_f32_e32 v7, v7
	v_writelane_b32 v255, s0, 8
	s_ashr_i32 s0, s4, 31
	v_writelane_b32 v255, s59, 9
	v_mul_f32_e32 v7, 0x4f7ffffe, v7
	v_cvt_u32_f32_e32 v7, v7
	v_add_lshl_u32 v4, v4, v5, 1
	v_mov_b32_e32 v5, v0
	v_add_lshl_u32 v2, v1, v2, 1
	v_readfirstlane_b32 s12, v7
	s_mul_i32 s3, s3, s12
	s_mul_hi_u32 s3, s12, s3
	s_add_i32 s12, s12, s3
	s_mul_hi_u32 s3, s1, s12
	s_mul_i32 s3, s3, s2
	s_sub_i32 s1, s1, s3
	s_sub_i32 s3, s1, s2
	s_cmp_ge_u32 s1, s2
	s_cselect_b32 s1, s3, s1
	s_sub_i32 s3, s1, s2
	s_cmp_ge_u32 s1, s2
	s_cselect_b32 s1, s3, s1
	s_xor_b32 s1, s1, s0
	s_sub_i32 s0, s1, s0
	s_cmp_lg_u32 s0, 0
	s_cselect_b64 s[0:1], -1, 0
	s_abs_i32 s59, s14
	v_cvt_f32_u32_e32 v7, s59
	v_writelane_b32 v255, s0, 28
	s_abs_i32 s57, s13
	s_abs_i32 s58, s15
	v_rcp_iflag_f32_e32 v7, v7
	v_writelane_b32 v255, s1, 29
	s_sub_i32 s0, 0, s59
	v_writelane_b32 v255, s14, 6
	v_mul_f32_e32 v7, 0x4f7ffffe, v7
	v_cvt_u32_f32_e32 v7, v7
	s_ashr_i32 s52, s79, 31
	s_lshl_b64 s[74:75], s[22:23], 1
	s_lshl_b64 s[76:77], s[20:21], 1
	v_readfirstlane_b32 s1, v7
	v_cvt_f32_u32_e32 v7, s57
	s_mul_i32 s0, s0, s1
	s_mul_hi_u32 s0, s1, s0
	s_add_i32 s0, s1, s0
	v_rcp_iflag_f32_e32 v7, v7
	v_writelane_b32 v255, s0, 23
	s_ashr_i32 s0, s13, 31
	v_writelane_b32 v255, s0, 32
	v_mul_f32_e32 v7, 0x4f7ffffe, v7
	v_cvt_u32_f32_e32 v7, v7
	s_sub_i32 s0, 0, s57
	v_mov_b32_e32 v3, v0
	s_mov_b32 s31, 0
	v_readfirstlane_b32 s1, v7
	v_cvt_f32_u32_e32 v7, s58
	s_mul_i32 s0, s0, s1
	s_mul_hi_u32 s0, s1, s0
	s_add_i32 s0, s1, s0
	v_rcp_iflag_f32_e32 v7, v7
	v_writelane_b32 v255, s0, 33
	s_ashr_i32 s0, s15, 31
	v_writelane_b32 v255, s0, 25
	v_mul_f32_e32 v7, 0x4f7ffffe, v7
	v_cvt_u32_f32_e32 v7, v7
	s_sub_i32 s0, 0, s58
	v_writelane_b32 v255, s15, 31
	v_cmp_eq_u32_e64 s[6:7], 0, v10
	v_readfirstlane_b32 s1, v7
	s_mul_i32 s0, s0, s1
	s_mul_hi_u32 s0, s1, s0
	s_add_i32 s0, s1, s0
	s_abs_i32 s1, s79
	v_cvt_f32_u32_e32 v7, s1
	v_writelane_b32 v255, s0, 24
	s_sub_i32 s18, 0, s1
	v_add_u32_e32 v166, 0, v11
	v_rcp_iflag_f32_e32 v7, v7
	s_barrier
	v_mul_f32_e32 v7, 0x4f7ffffe, v7
	v_cvt_u32_f32_e32 v165, v7
	s_nop 0
	v_readfirstlane_b32 s0, v165
	s_mul_i32 s2, s18, s0
	s_mul_hi_u32 s2, s0, s2
	s_add_i32 s0, s0, s2
	s_add_u32 s2, s46, s20
	s_addc_u32 s3, s47, s21
	v_lshl_add_u64 v[138:139], s[2:3], 0, v[4:5]
	v_lshl_add_u64 v[140:141], s[2:3], 0, v[2:3]
	s_branch .LBB0_169

; template <int MODE> __device__ __forceinline__ void gemm_phase(LAS unsigned char* lds, const GD& g, const int tid) {
;     ...
;         if (!has_next) break;
; #pragma unroll
;         for (int a = 0; a < 2; ++a)
; #pragma unroll
;             for (int b = 0; b < 2; ++b)
; #pragma unroll
;                 for (int m = 0; m < 4; ++m)
; #pragma unroll
;                     for (int n = 0; n < 2; ++n) acc[a][b][m][n] = (f32x4){0.f, 0.f, 0.f, 0.f};
;         cur = nxt; cA = nA; cB = nB; ++ui; rsv_load(rsv, g, cur, wr, fr);
.LBB0_186:
	s_andn2_b64 vcc, exec, s[50:51]
	s_cbranch_vccnz .LBB0_193
	s_and_b64 s[2:3], s[92:93], exec
	s_cselect_b32 s95, s79, s9
	s_cselect_b32 s94, s78, s8
	s_cselect_b32 s65, s87, s69
	s_cselect_b32 s64, s86, s68
	s_add_u32 s68, s68, s74
	s_waitcnt lgkmcnt(0)
	v_mov_b32_e32 v2, 0
	s_addc_u32 s69, s69, s75
	s_mov_b32 s12, 0
	v_mov_b32_e32 v3, v2
	v_mov_b32_e32 v4, v2
	v_mov_b32_e32 v5, v2
	v_mov_b32_e32 v6, v2
	v_mov_b32_e32 v7, v2
	v_mov_b32_e32 v8, v2
	v_mov_b32_e32 v9, v2
	v_mov_b32_e32 v18, v2
	v_mov_b32_e32 v19, v2
	v_mov_b32_e32 v20, v2
	v_mov_b32_e32 v21, v2
	v_mov_b32_e32 v22, v2
	v_mov_b32_e32 v23, v2
	v_mov_b32_e32 v24, v2
	v_mov_b32_e32 v25, v2
	v_mov_b32_e32 v34, v2
	v_mov_b32_e32 v35, v2
	v_mov_b32_e32 v36, v2
	v_mov_b32_e32 v37, v2
	v_mov_b32_e32 v38, v2
	v_mov_b32_e32 v39, v2
	v_mov_b32_e32 v40, v2
	v_mov_b32_e32 v41, v2
	v_mov_b32_e32 v50, v2
	v_mov_b32_e32 v51, v2
	v_mov_b32_e32 v52, v2
	v_mov_b32_e32 v53, v2
	v_mov_b32_e32 v54, v2
	v_mov_b32_e32 v55, v2
	v_mov_b32_e32 v56, v2
	v_mov_b32_e32 v57, v2
	v_mov_b32_e32 v10, v2
	v_mov_b32_e32 v11, v2
	v_mov_b32_e32 v12, v2
	v_mov_b32_e32 v13, v2
	v_mov_b32_e32 v14, v2
	v_mov_b32_e32 v15, v2
	v_mov_b32_e32 v16, v2
	v_mov_b32_e32 v17, v2
	v_mov_b32_e32 v26, v2
	v_mov_b32_e32 v27, v2
	v_mov_b32_e32 v28, v2
	v_mov_b32_e32 v29, v2
	v_mov_b32_e32 v30, v2
	v_mov_b32_e32 v31, v2
	v_mov_b32_e32 v32, v2
	v_mov_b32_e32 v33, v2
	v_mov_b32_e32 v42, v2
	v_mov_b32_e32 v43, v2
	v_mov_b32_e32 v44, v2
	v_mov_b32_e32 v45, v2
	v_mov_b32_e32 v46, v2
	v_mov_b32_e32 v47, v2
	v_mov_b32_e32 v48, v2
	v_mov_b32_e32 v49, v2
	v_mov_b32_e32 v58, v2
	v_mov_b32_e32 v59, v2
	v_mov_b32_e32 v60, v2
	v_mov_b32_e32 v61, v2
	v_mov_b32_e32 v62, v2
	v_mov_b32_e32 v63, v2
	v_mov_b32_e32 v64, v2
	v_mov_b32_e32 v65, v2
	v_mov_b32_e32 v66, v2
	v_mov_b32_e32 v67, v2
	v_mov_b32_e32 v68, v2
	v_mov_b32_e32 v69, v2
	v_mov_b32_e32 v70, v2
	v_mov_b32_e32 v71, v2
	v_mov_b32_e32 v72, v2
	v_mov_b32_e32 v73, v2
	v_mov_b32_e32 v82, v2
	v_mov_b32_e32 v83, v2
	v_mov_b32_e32 v84, v2
	v_mov_b32_e32 v85, v2
	v_mov_b32_e32 v86, v2
	v_mov_b32_e32 v87, v2
	v_mov_b32_e32 v88, v2
	v_mov_b32_e32 v89, v2
	v_mov_b32_e32 v98, v2
	v_mov_b32_e32 v99, v2
	v_mov_b32_e32 v100, v2
	v_mov_b32_e32 v101, v2
	v_mov_b32_e32 v102, v2
	v_mov_b32_e32 v103, v2
	v_mov_b32_e32 v104, v2
	v_mov_b32_e32 v105, v2
	v_mov_b32_e32 v114, v2
	v_mov_b32_e32 v115, v2
	v_mov_b32_e32 v116, v2
	v_mov_b32_e32 v117, v2
	v_mov_b32_e32 v118, v2
	v_mov_b32_e32 v119, v2
	v_mov_b32_e32 v120, v2
	v_mov_b32_e32 v121, v2
	v_mov_b32_e32 v74, v2
	v_mov_b32_e32 v75, v2
	v_mov_b32_e32 v76, v2
	v_mov_b32_e32 v77, v2
	v_mov_b32_e32 v78, v2
	v_mov_b32_e32 v79, v2
	v_mov_b32_e32 v80, v2
	v_mov_b32_e32 v81, v2
	v_mov_b32_e32 v90, v2
	v_mov_b32_e32 v91, v2
	v_mov_b32_e32 v92, v2
	v_mov_b32_e32 v93, v2
	v_mov_b32_e32 v94, v2
	v_mov_b32_e32 v95, v2
	v_mov_b32_e32 v96, v2
	v_mov_b32_e32 v97, v2
	v_mov_b32_e32 v106, v2
	v_mov_b32_e32 v107, v2
	v_mov_b32_e32 v108, v2
	v_mov_b32_e32 v109, v2
	v_mov_b32_e32 v110, v2
	v_mov_b32_e32 v111, v2
	v_mov_b32_e32 v112, v2
	v_mov_b32_e32 v113, v2
	v_mov_b32_e32 v122, v2
	v_mov_b32_e32 v123, v2
	v_mov_b32_e32 v124, v2
	v_mov_b32_e32 v125, v2
	v_mov_b32_e32 v126, v2
	v_mov_b32_e32 v127, v2
	v_mov_b32_e32 v128, v2
	v_mov_b32_e32 v129, v2
	s_branch .Lpeel188_189

; #define PG8_STAGE(bufoff, gbase, voff) do { _Pragma("unroll") for (int _i = 0; _i < 2; ++_i) \
;         __builtin_amdgcn_global_load_lds((const unsigned*)((const char*)(gbase) + (voff)[_i]), (LAS unsigned*)(lds + (bufoff) + ldsw + _i * 8192), 16, 0, 0); } while (0)
; #define PG8_LDA(dst, b, h) do { _Pragma("unroll") for (int m = 0; m < 4; ++m) _Pragma("unroll") for (int k = 0; k < 2; ++k) dst[m][k] = *(const LAS bf16x8*)(lds + PG8_SA(b, h) + aoff + m * 2048 + k * 1024); } while (0)
; #define PG8_LDB(dst, b, h) do { _Pragma("unroll") for (int n = 0; n < 2; ++n) _Pragma("unroll") for (int k = 0; k < 2; ++k) dst[n][k] = *(const LAS bf16x8*)(lds + PG8_SB(b, h) + boff + n * 2048 + k * 1024); } while (0)
; #define PG8_MMA(ai, bj, At, Bt) do { __builtin_amdgcn_s_setprio(1); _Pragma("unroll") for (int m = 0; m < 4; ++m) _Pragma("unroll") for (int n = 0; n < 2; ++n) _Pragma("unroll") for (int k = 0; k < 2; ++k) \
;         acc[ai][bj][m][n] = __builtin_amdgcn_mfma_f32_16x16x32_bf16(Bt[n][k], At[m][k], acc[ai][bj][m][n], 0, 0, 0); __builtin_amdgcn_s_setprio(0); } while (0)
; #define PG8_WAIT_V(n) asm volatile("s_waitcnt vmcnt(" #n ")" ::: "memory")
; #define PG8_WAIT_L(n) asm volatile("s_waitcnt lgkmcnt(" #n ")" ::: "memory")
; #define PG8_BAR __builtin_amdgcn_s_barrier()
; #define PG8_SCHED __builtin_amdgcn_sched_barrier(0)
; template <int MODE> __device__ __forceinline__ void gemm_phase(LAS unsigned char* lds, const GD& g, const int tid) {
;     ...
;         for (int t = 0; t < nt; t += 2) {
;             const bool last = (t == nt - 2);
;             const char* a1 = cA + (size_t)(t + 1) * kstA;
;             const char* a2 = last ? nA : cA + (size_t)(t + 2) * kstA; const char* b2 = last ? nB : cB + (size_t)(t + 2) * kstB;
;             const char* a3 = a2 + kstA; const char* b3 = b2 + kstB;
;             PG8_LDB(B0, 0, 0); PG8_LDB(B1, 0, 1); PG8_SCHED; PG8_LDA(At, 0, 0); PG8_STAGE(PG8_SA(1, 1), a1 + hsA, voffA);
;             PG8_WAIT_V(8); PG8_WAIT_L(0); PG8_BAR; PG8_MMA(0, 0, At, B0); PG8_MMA(0, 1, At, B1); PG8_BAR; PG8_SCHED;
;             PG8_LDA(At, 0, 1); PG8_STAGE(PG8_SB(0, 0), b2, voffB); PG8_STAGE(PG8_SB(0, 1), b2 + hsB, voffB); PG8_STAGE(PG8_SA(0, 0), a2, voffA);
;             PG8_WAIT_V(8); PG8_WAIT_L(0); PG8_BAR; PG8_MMA(1, 0, At, B0); PG8_MMA(1, 1, At, B1); PG8_BAR; PG8_SCHED;
.Lpeel188_188:
	s_add_i32 s12, s12, 2
	s_add_u32 vcc_lo, s2, s20
	s_addc_u32 vcc_hi, s3, s21
	s_add_i32 s13, 0, 0x10000
	v_add_u32_e32 v1, s13, v163
	s_add_i32 s81, 0, 0x14000
	s_waitcnt lgkmcnt(0)
	ds_read_b128 v[142:145], v1
	ds_read_b128 v[146:149], v1 offset:1024
	ds_read_b128 v[150:153], v1 offset:2048
	ds_read_b128 v[168:171], v1 offset:3072
	v_add_u32_e32 v1, s81, v163
	ds_read_b128 v[172:175], v1
	ds_read_b128 v[176:179], v1 offset:1024
	ds_read_b128 v[180:183], v1 offset:2048
	ds_read_b128 v[184:187], v1 offset:3072
	v_lshl_add_u64 v[192:193], s[8:9], 0, v[140:141]
	s_add_i32 m0, s17, 0xc000
	ds_read_b128 v[188:191], v166
	ds_read_b128 v[196:199], v166 offset:1024
	ds_read_b128 v[204:207], v166 offset:2048
	ds_read_b128 v[220:223], v166 offset:3072
	ds_read_b128 v[224:227], v166 offset:4096
	ds_read_b128 v[228:231], v166 offset:5120
	ds_read_b128 v[232:235], v166 offset:6144
	ds_read_b128 v[236:239], v166 offset:7168
	global_load_lds_dwordx4 v[192:193], off
	v_lshl_add_u64 v[192:193], s[8:9], 0, v[138:139]
	s_add_i32 m0, s17, 0xe000
	s_nop 0
	global_load_lds_dwordx4 v[192:193], off
	s_waitcnt vmcnt(63)
	s_waitcnt lgkmcnt(0)
	s_barrier
	s_setprio 1
	s_waitcnt lgkmcnt(0)
	v_mfma_f32_16x16x32_bf16 v[126:129], v[142:145], v[188:191], v[126:129]
	v_mfma_f32_16x16x32_bf16 v[122:125], v[150:153], v[188:191], v[122:125]
	v_mfma_f32_16x16x32_bf16 v[110:113], v[142:145], v[204:207], v[110:113]
	v_mfma_f32_16x16x32_bf16 v[106:109], v[150:153], v[204:207], v[106:109]
	v_mfma_f32_16x16x32_bf16 v[94:97], v[142:145], v[224:227], v[94:97]
	v_mfma_f32_16x16x32_bf16 v[90:93], v[150:153], v[224:227], v[90:93]
	v_mfma_f32_16x16x32_bf16 v[78:81], v[142:145], v[232:235], v[78:81]
	v_mfma_f32_16x16x32_bf16 v[74:77], v[150:153], v[232:235], v[74:77]
	v_mfma_f32_16x16x32_bf16 v[126:129], v[146:149], v[196:199], v[126:129]
	v_mfma_f32_16x16x32_bf16 v[122:125], v[168:171], v[196:199], v[122:125]
	v_mfma_f32_16x16x32_bf16 v[110:113], v[146:149], v[220:223], v[110:113]
	v_mfma_f32_16x16x32_bf16 v[106:109], v[168:171], v[220:223], v[106:109]
	v_mfma_f32_16x16x32_bf16 v[94:97], v[146:149], v[228:231], v[94:97]
	v_mfma_f32_16x16x32_bf16 v[90:93], v[168:171], v[228:231], v[90:93]
	v_mfma_f32_16x16x32_bf16 v[78:81], v[146:149], v[236:239], v[78:81]
	v_mfma_f32_16x16x32_bf16 v[74:77], v[168:171], v[236:239], v[74:77]
	s_setprio 0
	s_setprio 1
	v_mfma_f32_16x16x32_bf16 v[118:121], v[172:175], v[188:191], v[118:121]
	v_mfma_f32_16x16x32_bf16 v[114:117], v[180:183], v[188:191], v[114:117]
	v_mfma_f32_16x16x32_bf16 v[102:105], v[172:175], v[204:207], v[102:105]
	v_mfma_f32_16x16x32_bf16 v[98:101], v[180:183], v[204:207], v[98:101]
	v_mfma_f32_16x16x32_bf16 v[86:89], v[172:175], v[224:227], v[86:89]
	v_mfma_f32_16x16x32_bf16 v[82:85], v[180:183], v[224:227], v[82:85]
	v_mfma_f32_16x16x32_bf16 v[70:73], v[172:175], v[232:235], v[70:73]
	v_mfma_f32_16x16x32_bf16 v[66:69], v[180:183], v[232:235], v[66:69]
	v_mfma_f32_16x16x32_bf16 v[118:121], v[176:179], v[196:199], v[118:121]
	v_mfma_f32_16x16x32_bf16 v[114:117], v[184:187], v[196:199], v[114:117]
	v_mfma_f32_16x16x32_bf16 v[102:105], v[176:179], v[220:223], v[102:105]
	v_mfma_f32_16x16x32_bf16 v[98:101], v[184:187], v[220:223], v[98:101]
	v_mfma_f32_16x16x32_bf16 v[86:89], v[176:179], v[228:231], v[86:89]
	v_mfma_f32_16x16x32_bf16 v[82:85], v[184:187], v[228:231], v[82:85]
	v_mfma_f32_16x16x32_bf16 v[70:73], v[176:179], v[236:239], v[70:73]
	v_mfma_f32_16x16x32_bf16 v[66:69], v[184:187], v[236:239], v[66:69]
	s_setprio 0
	s_barrier
	s_add_i32 s13, s13, s11
	v_lshl_add_u64 v[192:193], s[82:83], 0, v[132:133]
	s_mov_b32 m0, s13
	ds_read_b128 v[188:191], v166 offset:16384
	ds_read_b128 v[196:199], v166 offset:17408
	ds_read_b128 v[204:207], v166 offset:18432
	ds_read_b128 v[220:223], v166 offset:19456
	ds_read_b128 v[224:227], v166 offset:20480
	ds_read_b128 v[228:231], v166 offset:21504
	ds_read_b128 v[232:235], v166 offset:22528
	ds_read_b128 v[236:239], v166 offset:23552
	global_load_lds_dwordx4 v[192:193], off
	s_add_i32 m0, s13, 0x2000
	s_add_u32 s60, s82, s48
	v_lshl_add_u64 v[192:193], s[82:83], 0, v[136:137]
	s_addc_u32 s61, s83, s49
	s_add_i32 s13, s81, s11
	global_load_lds_dwordx4 v[192:193], off
	v_lshl_add_u64 v[192:193], s[60:61], 0, v[132:133]
	s_mov_b32 m0, s13
	s_nop 0
	global_load_lds_dwordx4 v[192:193], off
	v_lshl_add_u64 v[192:193], s[60:61], 0, v[136:137]
	s_add_i32 m0, s13, 0x2000
	s_nop 0
	global_load_lds_dwordx4 v[192:193], off
	v_lshl_add_u64 v[192:193], s[2:3], 0, v[130:131]
	s_mov_b32 m0, s17
	s_nop 0
	global_load_lds_dwordx4 v[192:193], off
	v_lshl_add_u64 v[192:193], s[2:3], 0, v[134:135]
	s_mov_b32 m0, s24
	s_nop 0
	global_load_lds_dwordx4 v[192:193], off
	s_waitcnt vmcnt(63)
	s_waitcnt lgkmcnt(0)
	s_barrier
; #define PG8_STAGE(bufoff, gbase, voff) do { _Pragma("unroll") for (int _i = 0; _i < 2; ++_i) \
;         __builtin_amdgcn_global_load_lds((const unsigned*)((const char*)(gbase) + (voff)[_i]), (LAS unsigned*)(lds + (bufoff) + ldsw + _i * 8192), 16, 0, 0); } while (0)
; #define PG8_LDA(dst, b, h) do { _Pragma("unroll") for (int m = 0; m < 4; ++m) _Pragma("unroll") for (int k = 0; k < 2; ++k) dst[m][k] = *(const LAS bf16x8*)(lds + PG8_SA(b, h) + aoff + m * 2048 + k * 1024); } while (0)
; #define PG8_LDB(dst, b, h) do { _Pragma("unroll") for (int n = 0; n < 2; ++n) _Pragma("unroll") for (int k = 0; k < 2; ++k) dst[n][k] = *(const LAS bf16x8*)(lds + PG8_SB(b, h) + boff + n * 2048 + k * 1024); } while (0)
; #define PG8_MMA(ai, bj, At, Bt) do { __builtin_amdgcn_s_setprio(1); _Pragma("unroll") for (int m = 0; m < 4; ++m) _Pragma("unroll") for (int n = 0; n < 2; ++n) _Pragma("unroll") for (int k = 0; k < 2; ++k) \
;         acc[ai][bj][m][n] = __builtin_amdgcn_mfma_f32_16x16x32_bf16(Bt[n][k], At[m][k], acc[ai][bj][m][n], 0, 0, 0); __builtin_amdgcn_s_setprio(0); } while (0)
; #define PG8_WAIT_V(n) asm volatile("s_waitcnt vmcnt(" #n ")" ::: "memory")
; #define PG8_WAIT_L(n) asm volatile("s_waitcnt lgkmcnt(" #n ")" ::: "memory")
; #define PG8_BAR __builtin_amdgcn_s_barrier()
; #define PG8_SCHED __builtin_amdgcn_sched_barrier(0)
; template <int MODE> __device__ __forceinline__ void gemm_phase(LAS unsigned char* lds, const GD& g, const int tid) {
;     ...
;             PG8_WAIT_V(8); PG8_WAIT_L(0); PG8_BAR; PG8_MMA(1, 0, At, B0); PG8_MMA(1, 1, At, B1); PG8_BAR; PG8_SCHED;
;             PG8_LDB(B0, 1, 0); PG8_LDB(B1, 1, 1); PG8_SCHED; PG8_LDA(At, 1, 0); PG8_STAGE(PG8_SA(0, 1), a2 + hsA, voffA);
;             PG8_WAIT_V(8); PG8_WAIT_L(0); PG8_BAR; PG8_MMA(0, 0, At, B0); PG8_MMA(0, 1, At, B1); PG8_BAR; PG8_SCHED;
	s_setprio 1
	s_waitcnt lgkmcnt(0)
	v_mfma_f32_16x16x32_bf16 v[62:65], v[142:145], v[188:191], v[62:65]
	v_mfma_f32_16x16x32_bf16 v[58:61], v[150:153], v[188:191], v[58:61]
	v_mfma_f32_16x16x32_bf16 v[46:49], v[142:145], v[204:207], v[46:49]
	v_mfma_f32_16x16x32_bf16 v[42:45], v[150:153], v[204:207], v[42:45]
	v_mfma_f32_16x16x32_bf16 v[30:33], v[142:145], v[224:227], v[30:33]
	v_mfma_f32_16x16x32_bf16 v[26:29], v[150:153], v[224:227], v[26:29]
	v_mfma_f32_16x16x32_bf16 v[14:17], v[142:145], v[232:235], v[14:17]
	v_mfma_f32_16x16x32_bf16 v[10:13], v[150:153], v[232:235], v[10:13]
	v_mfma_f32_16x16x32_bf16 v[62:65], v[146:149], v[196:199], v[62:65]
	v_mfma_f32_16x16x32_bf16 v[58:61], v[168:171], v[196:199], v[58:61]
	v_mfma_f32_16x16x32_bf16 v[46:49], v[146:149], v[220:223], v[46:49]
	v_mfma_f32_16x16x32_bf16 v[42:45], v[168:171], v[220:223], v[42:45]
	v_mfma_f32_16x16x32_bf16 v[30:33], v[146:149], v[228:231], v[30:33]
	v_mfma_f32_16x16x32_bf16 v[26:29], v[168:171], v[228:231], v[26:29]
	v_mfma_f32_16x16x32_bf16 v[14:17], v[146:149], v[236:239], v[14:17]
	v_mfma_f32_16x16x32_bf16 v[10:13], v[168:171], v[236:239], v[10:13]
	s_setprio 0
	s_setprio 1
	v_mfma_f32_16x16x32_bf16 v[54:57], v[172:175], v[188:191], v[54:57]
	v_mfma_f32_16x16x32_bf16 v[50:53], v[180:183], v[188:191], v[50:53]
	v_mfma_f32_16x16x32_bf16 v[38:41], v[172:175], v[204:207], v[38:41]
	v_mfma_f32_16x16x32_bf16 v[34:37], v[180:183], v[204:207], v[34:37]
	v_mfma_f32_16x16x32_bf16 v[22:25], v[172:175], v[224:227], v[22:25]
	v_mfma_f32_16x16x32_bf16 v[18:21], v[180:183], v[224:227], v[18:21]
	v_mfma_f32_16x16x32_bf16 v[6:9], v[172:175], v[232:235], v[6:9]
	v_mfma_f32_16x16x32_bf16 v[2:5], v[180:183], v[232:235], v[2:5]
	v_mfma_f32_16x16x32_bf16 v[54:57], v[176:179], v[196:199], v[54:57]
	v_mfma_f32_16x16x32_bf16 v[50:53], v[184:187], v[196:199], v[50:53]
	v_mfma_f32_16x16x32_bf16 v[38:41], v[176:179], v[220:223], v[38:41]
	v_mfma_f32_16x16x32_bf16 v[34:37], v[184:187], v[220:223], v[34:37]
	v_mfma_f32_16x16x32_bf16 v[22:25], v[176:179], v[228:231], v[22:25]
	v_mfma_f32_16x16x32_bf16 v[18:21], v[184:187], v[228:231], v[18:21]
	v_mfma_f32_16x16x32_bf16 v[6:9], v[176:179], v[236:239], v[6:9]
	v_mfma_f32_16x16x32_bf16 v[2:5], v[184:187], v[236:239], v[2:5]
	s_setprio 0
	s_barrier
	s_add_i32 s13, 0, 0x18000
	v_add_u32_e32 v1, s13, v163
	s_add_i32 s60, 0, 0x1c000
	ds_read_b128 v[142:145], v1
	ds_read_b128 v[146:149], v1 offset:1024
	ds_read_b128 v[150:153], v1 offset:2048
	ds_read_b128 v[168:171], v1 offset:3072
	v_add_u32_e32 v1, s60, v163
	ds_read_b128 v[172:175], v1
	ds_read_b128 v[176:179], v1 offset:1024
	ds_read_b128 v[180:183], v1 offset:2048
	ds_read_b128 v[184:187], v1 offset:3072
	s_add_u32 s2, s2, s46
	s_addc_u32 s3, s3, s47
	s_mov_b32 m0, s25
	v_lshl_add_u64 v[192:193], s[2:3], 0, v[130:131]
	ds_read_b128 v[188:191], v166 offset:32768
	ds_read_b128 v[196:199], v166 offset:33792
	ds_read_b128 v[204:207], v166 offset:34816
	ds_read_b128 v[220:223], v166 offset:35840
	ds_read_b128 v[224:227], v166 offset:36864
	ds_read_b128 v[228:231], v166 offset:37888
	ds_read_b128 v[232:235], v166 offset:38912
	ds_read_b128 v[236:239], v166 offset:39936
	global_load_lds_dwordx4 v[192:193], off
	v_lshl_add_u64 v[192:193], s[2:3], 0, v[134:135]
	s_mov_b32 m0, s26
	s_nop 0
	global_load_lds_dwordx4 v[192:193], off
	s_waitcnt vmcnt(8)
	s_waitcnt lgkmcnt(0)
	s_barrier
	s_setprio 1
	s_waitcnt lgkmcnt(0)
	v_mfma_f32_16x16x32_bf16 v[126:129], v[142:145], v[188:191], v[126:129]
	v_mfma_f32_16x16x32_bf16 v[122:125], v[150:153], v[188:191], v[122:125]
	v_mfma_f32_16x16x32_bf16 v[110:113], v[142:145], v[204:207], v[110:113]
	v_mfma_f32_16x16x32_bf16 v[106:109], v[150:153], v[204:207], v[106:109]
	v_mfma_f32_16x16x32_bf16 v[94:97], v[142:145], v[224:227], v[94:97]
	v_mfma_f32_16x16x32_bf16 v[90:93], v[150:153], v[224:227], v[90:93]
	v_mfma_f32_16x16x32_bf16 v[78:81], v[142:145], v[232:235], v[78:81]
	v_mfma_f32_16x16x32_bf16 v[74:77], v[150:153], v[232:235], v[74:77]
	v_mfma_f32_16x16x32_bf16 v[126:129], v[146:149], v[196:199], v[126:129]
	v_mfma_f32_16x16x32_bf16 v[122:125], v[168:171], v[196:199], v[122:125]
	v_mfma_f32_16x16x32_bf16 v[110:113], v[146:149], v[220:223], v[110:113]
	v_mfma_f32_16x16x32_bf16 v[106:109], v[168:171], v[220:223], v[106:109]
	v_mfma_f32_16x16x32_bf16 v[94:97], v[146:149], v[228:231], v[94:97]
	v_mfma_f32_16x16x32_bf16 v[90:93], v[168:171], v[228:231], v[90:93]
	v_mfma_f32_16x16x32_bf16 v[78:81], v[146:149], v[236:239], v[78:81]
	v_mfma_f32_16x16x32_bf16 v[74:77], v[168:171], v[236:239], v[74:77]
	s_setprio 0
	s_setprio 1
	v_mfma_f32_16x16x32_bf16 v[118:121], v[172:175], v[188:191], v[118:121]
	v_mfma_f32_16x16x32_bf16 v[114:117], v[180:183], v[188:191], v[114:117]
	v_mfma_f32_16x16x32_bf16 v[102:105], v[172:175], v[204:207], v[102:105]
	v_mfma_f32_16x16x32_bf16 v[98:101], v[180:183], v[204:207], v[98:101]
	v_mfma_f32_16x16x32_bf16 v[86:89], v[172:175], v[224:227], v[86:89]
	v_mfma_f32_16x16x32_bf16 v[82:85], v[180:183], v[224:227], v[82:85]
	v_mfma_f32_16x16x32_bf16 v[70:73], v[172:175], v[232:235], v[70:73]
	v_mfma_f32_16x16x32_bf16 v[66:69], v[180:183], v[232:235], v[66:69]
	v_mfma_f32_16x16x32_bf16 v[118:121], v[176:179], v[196:199], v[118:121]
	v_mfma_f32_16x16x32_bf16 v[114:117], v[184:187], v[196:199], v[114:117]
	v_mfma_f32_16x16x32_bf16 v[102:105], v[176:179], v[220:223], v[102:105]
	v_mfma_f32_16x16x32_bf16 v[98:101], v[184:187], v[220:223], v[98:101]
	v_mfma_f32_16x16x32_bf16 v[86:89], v[176:179], v[228:231], v[86:89]
	v_mfma_f32_16x16x32_bf16 v[82:85], v[184:187], v[228:231], v[82:85]
	v_mfma_f32_16x16x32_bf16 v[70:73], v[176:179], v[236:239], v[70:73]
	v_mfma_f32_16x16x32_bf16 v[66:69], v[184:187], v[236:239], v[66:69]
	s_setprio 0
	s_barrier
; #define PG8_STAGE(bufoff, gbase, voff) do { _Pragma("unroll") for (int _i = 0; _i < 2; ++_i) \
;         __builtin_amdgcn_global_load_lds((const unsigned*)((const char*)(gbase) + (voff)[_i]), (LAS unsigned*)(lds + (bufoff) + ldsw + _i * 8192), 16, 0, 0); } while (0)
; #define PG8_LDA(dst, b, h) do { _Pragma("unroll") for (int m = 0; m < 4; ++m) _Pragma("unroll") for (int k = 0; k < 2; ++k) dst[m][k] = *(const LAS bf16x8*)(lds + PG8_SA(b, h) + aoff + m * 2048 + k * 1024); } while (0)
; #define PG8_MMA(ai, bj, At, Bt) do { __builtin_amdgcn_s_setprio(1); _Pragma("unroll") for (int m = 0; m < 4; ++m) _Pragma("unroll") for (int n = 0; n < 2; ++n) _Pragma("unroll") for (int k = 0; k < 2; ++k) \
;         acc[ai][bj][m][n] = __builtin_amdgcn_mfma_f32_16x16x32_bf16(Bt[n][k], At[m][k], acc[ai][bj][m][n], 0, 0, 0); __builtin_amdgcn_s_setprio(0); } while (0)
; #define PG8_WAIT_V(n) asm volatile("s_waitcnt vmcnt(" #n ")" ::: "memory")
; #define PG8_WAIT_L(n) asm volatile("s_waitcnt lgkmcnt(" #n ")" ::: "memory")
; #define PG8_BAR __builtin_amdgcn_s_barrier()
; #define PG8_SCHED __builtin_amdgcn_sched_barrier(0)
; template <int MODE> __device__ __forceinline__ void gemm_phase(LAS unsigned char* lds, const GD& g, const int tid) {
;     ...
;             PG8_LDA(At, 1, 1); PG8_STAGE(PG8_SB(1, 0), b3, voffB); PG8_STAGE(PG8_SB(1, 1), b3 + hsB, voffB); PG8_STAGE(PG8_SA(1, 0), a3, voffA);
;             PG8_WAIT_V(8); PG8_WAIT_L(0); PG8_BAR; PG8_MMA(1, 0, At, B0); PG8_MMA(1, 1, At, B1); PG8_BAR; PG8_SCHED;
;         }
	s_add_u32 s2, s82, s22
	s_addc_u32 s3, s83, s23
	s_add_i32 s13, s13, s11
	v_lshl_add_u64 v[192:193], s[2:3], 0, v[132:133]
	s_mov_b32 m0, s13
	ds_read_b128 v[188:191], v166 offset:49152
	ds_read_b128 v[196:199], v166 offset:50176
	ds_read_b128 v[204:207], v166 offset:51200
	ds_read_b128 v[220:223], v166 offset:52224
	ds_read_b128 v[224:227], v166 offset:53248
	ds_read_b128 v[228:231], v166 offset:54272
	ds_read_b128 v[232:235], v166 offset:55296
	ds_read_b128 v[236:239], v166 offset:56320
	global_load_lds_dwordx4 v[192:193], off
	s_add_i32 m0, s13, 0x2000
	v_lshl_add_u64 v[192:193], s[2:3], 0, v[136:137]
	s_add_u32 s2, s2, s48
	s_addc_u32 s3, s3, s49
	s_add_i32 s13, s60, s11
	global_load_lds_dwordx4 v[192:193], off
	v_lshl_add_u64 v[192:193], s[2:3], 0, v[132:133]
	s_mov_b32 m0, s13
	s_nop 0
	global_load_lds_dwordx4 v[192:193], off
	v_lshl_add_u64 v[192:193], s[2:3], 0, v[136:137]
	s_add_i32 m0, s13, 0x2000
	s_nop 0
	global_load_lds_dwordx4 v[192:193], off
	v_lshl_add_u64 v[192:193], vcc, 0, v[130:131]
	s_mov_b32 m0, s28
	s_nop 0
	global_load_lds_dwordx4 v[192:193], off
	v_lshl_add_u64 v[192:193], vcc, 0, v[134:135]
	s_mov_b32 m0, s29
	s_nop 0
	global_load_lds_dwordx4 v[192:193], off
	s_waitcnt vmcnt(8)
	s_waitcnt lgkmcnt(0)
	s_barrier
	s_setprio 1
	s_waitcnt lgkmcnt(0)
	v_mfma_f32_16x16x32_bf16 v[62:65], v[142:145], v[188:191], v[62:65]
	v_mfma_f32_16x16x32_bf16 v[58:61], v[150:153], v[188:191], v[58:61]
	v_mfma_f32_16x16x32_bf16 v[46:49], v[142:145], v[204:207], v[46:49]
	v_mfma_f32_16x16x32_bf16 v[42:45], v[150:153], v[204:207], v[42:45]
	v_mfma_f32_16x16x32_bf16 v[30:33], v[142:145], v[224:227], v[30:33]
	v_mfma_f32_16x16x32_bf16 v[26:29], v[150:153], v[224:227], v[26:29]
	v_mfma_f32_16x16x32_bf16 v[14:17], v[142:145], v[232:235], v[14:17]
	v_mfma_f32_16x16x32_bf16 v[10:13], v[150:153], v[232:235], v[10:13]
	v_mfma_f32_16x16x32_bf16 v[62:65], v[146:149], v[196:199], v[62:65]
	v_mfma_f32_16x16x32_bf16 v[58:61], v[168:171], v[196:199], v[58:61]
	v_mfma_f32_16x16x32_bf16 v[46:49], v[146:149], v[220:223], v[46:49]
	v_mfma_f32_16x16x32_bf16 v[42:45], v[168:171], v[220:223], v[42:45]
	v_mfma_f32_16x16x32_bf16 v[30:33], v[146:149], v[228:231], v[30:33]
	v_mfma_f32_16x16x32_bf16 v[26:29], v[168:171], v[228:231], v[26:29]
	v_mfma_f32_16x16x32_bf16 v[14:17], v[146:149], v[236:239], v[14:17]
	v_mfma_f32_16x16x32_bf16 v[10:13], v[168:171], v[236:239], v[10:13]
	s_setprio 0
	s_setprio 1
	v_mfma_f32_16x16x32_bf16 v[54:57], v[172:175], v[188:191], v[54:57]
	v_mfma_f32_16x16x32_bf16 v[50:53], v[180:183], v[188:191], v[50:53]
	v_mfma_f32_16x16x32_bf16 v[38:41], v[172:175], v[204:207], v[38:41]
	v_mfma_f32_16x16x32_bf16 v[34:37], v[180:183], v[204:207], v[34:37]
	v_mfma_f32_16x16x32_bf16 v[22:25], v[172:175], v[224:227], v[22:25]
	v_mfma_f32_16x16x32_bf16 v[18:21], v[180:183], v[224:227], v[18:21]
	v_mfma_f32_16x16x32_bf16 v[6:9], v[172:175], v[232:235], v[6:9]
	v_mfma_f32_16x16x32_bf16 v[2:5], v[180:183], v[232:235], v[2:5]
	v_mfma_f32_16x16x32_bf16 v[54:57], v[176:179], v[196:199], v[54:57]
	v_mfma_f32_16x16x32_bf16 v[50:53], v[184:187], v[196:199], v[50:53]
	v_mfma_f32_16x16x32_bf16 v[38:41], v[176:179], v[220:223], v[38:41]
	v_mfma_f32_16x16x32_bf16 v[34:37], v[184:187], v[220:223], v[34:37]
	v_mfma_f32_16x16x32_bf16 v[22:25], v[176:179], v[228:231], v[22:25]
	v_mfma_f32_16x16x32_bf16 v[18:21], v[184:187], v[228:231], v[18:21]
	v_mfma_f32_16x16x32_bf16 v[6:9], v[176:179], v[236:239], v[6:9]
	v_mfma_f32_16x16x32_bf16 v[2:5], v[184:187], v[236:239], v[2:5]
	s_setprio 0
	s_barrier
	s_add_u32 s68, s68, s74
	s_addc_u32 s69, s69, s75
	s_add_u32 s8, s8, s76
	s_addc_u32 s9, s9, s77
	s_cmp_ge_i32 s12, s30
	s_cbranch_scc1 .LBB0_194
	s_branch .LBB0_189

; #define PG8_STAGE(bufoff, gbase, voff) do { _Pragma("unroll") for (int _i = 0; _i < 2; ++_i) \
;         __builtin_amdgcn_global_load_lds((const unsigned*)((const char*)(gbase) + (voff)[_i]), (LAS unsigned*)(lds + (bufoff) + ldsw + _i * 8192), 16, 0, 0); } while (0)
; #define PG8_WAIT_V(n) asm volatile("s_waitcnt vmcnt(" #n ")" ::: "memory")
; #define PG8_BAR __builtin_amdgcn_s_barrier()
; template <int MODE> __device__ __forceinline__ void gemm_phase(LAS unsigned char* lds, const GD& g, const int tid) {
;     ...
;     PG8_STAGE(PG8_SB(0, 0), cB, voffB); PG8_STAGE(PG8_SB(0, 1), cB + hsB, voffB); PG8_STAGE(PG8_SA(0, 0), cA, voffA); PG8_STAGE(PG8_SA(0, 1), cA + hsA, voffA);
;     if (wr == 1) PG8_BAR;
;     PG8_WAIT_V(2); PG8_BAR;
;     PG8_STAGE(PG8_SB(1, 0), cB + kstB, voffB); PG8_STAGE(PG8_SA(1, 0), cA + kstA, voffA); PG8_STAGE(PG8_SB(1, 1), cB + hsB + kstB, voffB);
;     PG8_WAIT_V(6); PG8_BAR;
;     for (;;) {
;         const bool has_next = gd_next(g, ui + 1, nxt);
.LBB0_307:
	s_and_b32 s10, s4, 3
	s_ashr_i32 s4, s56, 31
	s_lshr_b32 s4, s4, 26
	v_bfe_u32 v7, v194, 4, 2
	s_add_i32 s4, s56, s4
	s_ashr_i32 s92, s4, 6
	v_lshlrev_b32_e32 v8, 6, v163
	v_lshlrev_b32_e32 v10, 4, v7
	s_movk_i32 s4, 0x3c0
	v_lshlrev_b32_e32 v9, 2, v163
	v_and_or_b32 v8, v8, s4, v10
	s_lshl_b32 s4, s5, 13
	v_and_b32_e32 v9, 32, v9
	v_bitop3_b32 v11, v8, s4, v9 bitop3:0xde
	v_lshlrev_b32_e32 v9, 2, v162
	s_ashr_i32 s21, s20, 31
	s_ashr_i32 s23, s22, 31
	v_lshl_or_b32 v8, v162, 6, v10
	s_lshl_b32 s4, s10, 12
	v_and_b32_e32 v9, 32, v9
	v_bitop3_b32 v173, s4, v8, v9 bitop3:0xf6
	s_add_u32 s4, s8, s22
	v_mov_b32_e32 v133, v0
	s_addc_u32 s5, s9, s23
	s_add_i32 m0, s26, 0x18000
	v_lshl_add_u64 v[8:9], s[4:5], 0, v[132:133]
	v_mov_b32_e32 v137, v0
	s_waitcnt vmcnt(2)
	s_barrier
	global_load_lds_dwordx4 v[8:9], off
	s_add_i32 m0, s26, 0x1a000
	v_lshl_add_u64 v[8:9], s[4:5], 0, v[136:137]
	s_add_u32 s4, s6, s20
	v_mov_b32_e32 v131, v0
	s_addc_u32 s5, s7, s21
	s_add_i32 s93, s26, 0x8000
	s_add_i32 s86, s26, 0xa000
	v_mov_b32_e32 v135, v0
	global_load_lds_dwordx4 v[8:9], off
	v_lshl_add_u64 v[8:9], s[4:5], 0, v[130:131]
	s_mov_b32 m0, s93
	s_add_u32 s2, s2, s22
	global_load_lds_dwordx4 v[8:9], off
	v_lshl_add_u64 v[8:9], s[4:5], 0, v[134:135]
	s_mov_b32 m0, s86
	s_addc_u32 s3, s3, s23
	global_load_lds_dwordx4 v[8:9], off
	s_add_i32 m0, s26, 0x1c000
	v_lshl_add_u64 v[8:9], s[2:3], 0, v[132:133]
	global_load_lds_dwordx4 v[8:9], off
	s_add_i32 m0, s26, 0x1e000
	s_cmp_gt_i32 s56, 63
	s_cselect_b64 s[62:63], -1, 0
	s_add_i32 s87, s92, -2
	s_cmpk_lt_u32 s1, 0x100
	s_cselect_b64 s[70:71], -1, 0
	s_cmp_eq_u32 s10, 0
	v_lshl_add_u64 v[8:9], s[2:3], 0, v[136:137]
	v_writelane_b32 v254, s56, 62
	s_cselect_b64 s[2:3], -1, 0
	v_cmp_gt_u32_e32 vcc, 2, v7
	s_and_b64 s[74:75], s[2:3], vcc
	v_readlane_b32 s2, v254, 42
	v_readlane_b32 s1, v254, 60
	global_load_lds_dwordx4 v[8:9], off
	v_lshl_or_b32 v8, s10, 6, v10
	v_mov_b32_e32 v9, v0
	v_readlane_b32 s3, v254, 43
	s_cmp_lg_u32 s1, 1
	v_readlane_b32 s10, v254, 33
	v_lshl_add_u64 v[138:139], s[2:3], 0, v[8:9]
	s_cselect_b64 s[2:3], -1, 0
	s_mul_i32 s12, s13, s10
	v_writelane_b32 v255, s2, 16
	s_cmp_eq_u32 s10, 16
	s_mul_i32 s11, s1, s12
	v_writelane_b32 v255, s3, 17
	s_cselect_b64 s[2:3], -1, 0
	s_and_b32 s1, s13, 3
	s_cmp_eq_u32 s1, 0
	s_cselect_b64 s[4:5], -1, 0
	s_and_b64 s[2:3], s[2:3], s[4:5]
	s_and_b32 s1, s30, 7
	s_cmp_eq_u32 s1, 0
	s_cselect_b64 s[4:5], -1, 0
	s_and_b64 s[2:3], s[2:3], s[4:5]
	v_writelane_b32 v255, s2, 4
	s_and_b32 s1, s31, 7
	v_lshlrev_b32_e32 v8, 5, v7
	v_writelane_b32 v255, s3, 5
	s_xor_b64 s[2:3], s[2:3], -1
	v_writelane_b32 v255, s2, 20
	v_lshlrev_b32_e32 v172, 3, v7
	s_waitcnt vmcnt(0)
	v_add_u32_e32 v4, v6, v4
	v_writelane_b32 v255, s3, 21
	s_ashr_i32 s2, s30, 3
	s_mul_i32 s1, s2, s1
	s_lshr_b32 s2, s31, 3
	s_add_i32 s1, s1, s2
	v_writelane_b32 v255, s1, 27
	s_ashr_i32 s1, s12, 31
	v_writelane_b32 v255, s1, 24
	s_lshr_b32 s1, s1, 29
	s_add_i32 s1, s12, s1
	s_ashr_i32 s2, s1, 3
	s_and_b32 s1, s1, -8
	s_sub_i32 s81, s12, s1
	v_writelane_b32 v255, s2, 30
	s_add_i32 s1, s2, 1
	v_readlane_b32 s2, v254, 48
	v_readlane_b32 s3, v254, 49
	v_writelane_b32 v255, s1, 8
	v_writelane_b32 v255, s13, 9
	v_lshl_add_u64 v[140:141], s[2:3], 0, v[8:9]
	s_abs_i32 s3, s30
	v_cvt_f32_u32_e32 v7, s3
	s_sub_i32 s4, 0, s3
	s_abs_i32 s2, s11
	s_lshl_b32 s13, s13, 3
	v_rcp_iflag_f32_e32 v7, v7
	s_ashr_i32 s1, s11, 31
	v_add_u32_e32 v1, v3, v1
	v_add_lshl_u32 v4, v4, v5, 1
	v_mul_f32_e32 v7, 0x4f7ffffe, v7
	v_cvt_u32_f32_e32 v7, v7
	v_mov_b32_e32 v5, v0
	v_add_lshl_u32 v2, v1, v2, 1
	v_mov_b32_e32 v3, v0
	v_readfirstlane_b32 s5, v7
	s_mul_i32 s4, s4, s5
	s_mul_hi_u32 s4, s5, s4
	s_add_i32 s5, s5, s4
	s_mul_hi_u32 s4, s2, s5
	s_mul_i32 s4, s4, s3
	s_sub_i32 s2, s2, s4
	s_sub_i32 s4, s2, s3
	s_cmp_ge_u32 s2, s3
	s_cselect_b32 s2, s4, s2
	s_sub_i32 s4, s2, s3
	s_cmp_ge_u32 s2, s3
	s_cselect_b32 s2, s4, s2
	s_xor_b32 s2, s2, s1
	s_sub_i32 s1, s2, s1
	s_cmp_lg_u32 s1, 0
	s_cselect_b64 s[2:3], -1, 0
	s_abs_i32 s5, s12
	v_cvt_f32_u32_e32 v7, s5
	v_writelane_b32 v255, s2, 28
	s_sub_i32 s1, 0, s5
	s_abs_i32 s77, s13
	v_rcp_iflag_f32_e32 v7, v7
	v_writelane_b32 v255, s3, 29
	s_lshl_b64 s[94:95], s[22:23], 1
	s_lshl_b64 s[42:43], s[20:21], 1
	v_mul_f32_e32 v7, 0x4f7ffffe, v7
	v_cvt_u32_f32_e32 v7, v7
	s_mov_b32 s78, 0
	v_or_b32_e32 v174, 1, v172
	v_or_b32_e32 v175, 2, v172
	v_readfirstlane_b32 s2, v7
	s_mul_i32 s1, s1, s2
	s_mul_hi_u32 s1, s2, s1
	s_add_i32 s1, s2, s1
	v_writelane_b32 v255, s1, 31
	s_ashr_i32 s1, s10, 31
	v_writelane_b32 v255, s1, 32
	s_abs_i32 s1, s10
	v_cvt_f32_u32_e32 v7, s1
	v_writelane_b32 v255, s1, 33
	s_sub_i32 s1, 0, s1
	v_or_b32_e32 v176, 3, v172
	v_rcp_iflag_f32_e32 v7, v7
	v_or_b32_e32 v177, 4, v172
	v_or_b32_e32 v178, 5, v172
	v_or_b32_e32 v179, 6, v172
	v_mul_f32_e32 v7, 0x4f7ffffe, v7
	v_cvt_u32_f32_e32 v7, v7
	v_or_b32_e32 v180, 7, v172
	s_mov_b32 s33, s11
	s_mov_b32 s56, s12
	v_readfirstlane_b32 s2, v7
	v_cvt_f32_u32_e32 v7, s77
	s_mul_i32 s1, s1, s2
	s_mul_hi_u32 s1, s2, s1
	s_add_i32 s1, s2, s1
	v_rcp_iflag_f32_e32 v7, v7
	v_writelane_b32 v255, s1, 35
	s_ashr_i32 s1, s13, 31
	v_writelane_b32 v255, s1, 23
	v_mul_f32_e32 v7, 0x4f7ffffe, v7
	v_cvt_u32_f32_e32 v7, v7
	s_sub_i32 s1, 0, s77
	s_mov_b32 s57, s13
	v_add_u32_e32 v182, 0, v11
	v_readfirstlane_b32 s2, v7
	s_mul_i32 s1, s1, s2
	s_mul_hi_u32 s1, s2, s1
	s_add_i32 s1, s2, s1
	v_writelane_b32 v255, s1, 25
	s_ashr_i32 s1, s79, 31
	s_abs_i32 s79, s79
	v_cvt_f32_u32_e32 v7, s79
	v_writelane_b32 v255, s1, 2
	s_sub_i32 s2, 0, s79
	s_mov_b32 s35, s2
	v_rcp_iflag_f32_e32 v7, v7
	s_barrier
	v_mul_f32_e32 v7, 0x4f7ffffe, v7
	v_cvt_u32_f32_e32 v181, v7
	s_nop 0
	v_readfirstlane_b32 s1, v181
	s_mul_i32 s2, s2, s1
	s_mul_hi_u32 s2, s1, s2
	s_add_i32 s1, s1, s2
	s_add_u32 s2, s46, s20
	s_addc_u32 s3, s47, s21
	v_writelane_b32 v255, s1, 6
	v_lshl_add_u64 v[142:143], s[2:3], 0, v[4:5]
	v_lshl_add_u64 v[144:145], s[2:3], 0, v[2:3]
	s_branch .LBB0_310

; template <int MODE> __device__ __forceinline__ void gemm_phase(LAS unsigned char* lds, const GD& g, const int tid) {
;     ...
;         for (int t = 0; t < nt; t += 2) {
;             const bool last = (t == nt - 2);
;             const char* a1 = cA + (size_t)(t + 1) * kstA;
;             const char* a2 = last ? nA : cA + (size_t)(t + 2) * kstA; const char* b2 = last ? nB : cB + (size_t)(t + 2) * kstB;
;     ...
;         if (!has_next) break;
; #pragma unroll
;         for (int a = 0; a < 2; ++a)
; #pragma unroll
;             for (int b = 0; b < 2; ++b)
; #pragma unroll
;                 for (int m = 0; m < 4; ++m)
; #pragma unroll
;                     for (int n = 0; n < 2; ++n) acc[a][b][m][n] = (f32x4){0.f, 0.f, 0.f, 0.f};
;         cur = nxt; cA = nA; cB = nB; ++ui; rsv_load(rsv, g, cur, wr, fr);
.LBB0_327:
	s_andn2_b64 vcc, exec, s[62:63]
	s_cbranch_vccnz .LBB0_334
	s_and_b64 s[2:3], s[52:53], exec
	s_cselect_b32 s3, s49, s7
	s_cselect_b32 s2, s48, s6
	s_cselect_b32 s83, s51, s9
	s_cselect_b32 s82, s50, s8
	s_add_u32 s8, s8, s94
	v_mov_b32_e32 v2, 0
	s_addc_u32 s9, s9, s95
	s_mov_b32 s1, 0
	v_mov_b32_e32 v3, v2
	v_mov_b32_e32 v4, v2
	v_mov_b32_e32 v5, v2
	v_mov_b32_e32 v6, v2
	v_mov_b32_e32 v7, v2
	v_mov_b32_e32 v8, v2
	v_mov_b32_e32 v9, v2
	v_mov_b32_e32 v10, v2
	v_mov_b32_e32 v11, v2
	v_mov_b32_e32 v12, v2
	v_mov_b32_e32 v13, v2
	v_mov_b32_e32 v18, v2
	v_mov_b32_e32 v19, v2
	v_mov_b32_e32 v20, v2
	v_mov_b32_e32 v21, v2
	v_mov_b32_e32 v26, v2
	v_mov_b32_e32 v27, v2
	v_mov_b32_e32 v28, v2
	v_mov_b32_e32 v29, v2
	v_mov_b32_e32 v34, v2
	v_mov_b32_e32 v35, v2
	v_mov_b32_e32 v36, v2
	v_mov_b32_e32 v37, v2
	v_mov_b32_e32 v42, v2
	v_mov_b32_e32 v43, v2
	v_mov_b32_e32 v44, v2
	v_mov_b32_e32 v45, v2
	v_mov_b32_e32 v50, v2
	v_mov_b32_e32 v51, v2
	v_mov_b32_e32 v52, v2
	v_mov_b32_e32 v53, v2
	v_mov_b32_e32 v14, v2
	v_mov_b32_e32 v15, v2
	v_mov_b32_e32 v16, v2
	v_mov_b32_e32 v17, v2
	v_mov_b32_e32 v22, v2
	v_mov_b32_e32 v23, v2
	v_mov_b32_e32 v24, v2
	v_mov_b32_e32 v25, v2
	v_mov_b32_e32 v30, v2
	v_mov_b32_e32 v31, v2
	v_mov_b32_e32 v32, v2
	v_mov_b32_e32 v33, v2
	v_mov_b32_e32 v38, v2
	v_mov_b32_e32 v39, v2
	v_mov_b32_e32 v40, v2
	v_mov_b32_e32 v41, v2
	v_mov_b32_e32 v46, v2
	v_mov_b32_e32 v47, v2
	v_mov_b32_e32 v48, v2
	v_mov_b32_e32 v49, v2
	v_mov_b32_e32 v54, v2
	v_mov_b32_e32 v55, v2
	v_mov_b32_e32 v56, v2
	v_mov_b32_e32 v57, v2
	v_mov_b32_e32 v58, v2
	v_mov_b32_e32 v59, v2
	v_mov_b32_e32 v60, v2
	v_mov_b32_e32 v61, v2
	v_mov_b32_e32 v62, v2
	v_mov_b32_e32 v63, v2
	v_mov_b32_e32 v64, v2
	v_mov_b32_e32 v65, v2
	v_mov_b32_e32 v66, v2
	v_mov_b32_e32 v67, v2
	v_mov_b32_e32 v68, v2
	v_mov_b32_e32 v69, v2
	v_mov_b32_e32 v70, v2
	v_mov_b32_e32 v71, v2
	v_mov_b32_e32 v72, v2
	v_mov_b32_e32 v73, v2
	v_mov_b32_e32 v74, v2
	v_mov_b32_e32 v75, v2
	v_mov_b32_e32 v76, v2
	v_mov_b32_e32 v77, v2
	v_mov_b32_e32 v82, v2
	v_mov_b32_e32 v83, v2
	v_mov_b32_e32 v84, v2
	v_mov_b32_e32 v85, v2
	v_mov_b32_e32 v90, v2
	v_mov_b32_e32 v91, v2
	v_mov_b32_e32 v92, v2
	v_mov_b32_e32 v93, v2
	v_mov_b32_e32 v98, v2
	v_mov_b32_e32 v99, v2
	v_mov_b32_e32 v100, v2
	v_mov_b32_e32 v101, v2
	v_mov_b32_e32 v106, v2
	v_mov_b32_e32 v107, v2
	v_mov_b32_e32 v108, v2
	v_mov_b32_e32 v109, v2
	v_mov_b32_e32 v114, v2
	v_mov_b32_e32 v115, v2
	v_mov_b32_e32 v116, v2
	v_mov_b32_e32 v117, v2
	v_mov_b32_e32 v78, v2
	v_mov_b32_e32 v79, v2
	v_mov_b32_e32 v80, v2
	v_mov_b32_e32 v81, v2
	v_mov_b32_e32 v86, v2
	v_mov_b32_e32 v87, v2
	v_mov_b32_e32 v88, v2
	v_mov_b32_e32 v89, v2
	v_mov_b32_e32 v94, v2
	v_mov_b32_e32 v95, v2
	v_mov_b32_e32 v96, v2
	v_mov_b32_e32 v97, v2
	v_mov_b32_e32 v102, v2
	v_mov_b32_e32 v103, v2
	v_mov_b32_e32 v104, v2
	v_mov_b32_e32 v105, v2
	v_mov_b32_e32 v110, v2
	v_mov_b32_e32 v111, v2
	v_mov_b32_e32 v112, v2
	v_mov_b32_e32 v113, v2
	v_mov_b32_e32 v118, v2
	v_mov_b32_e32 v119, v2
	v_mov_b32_e32 v120, v2
	v_mov_b32_e32 v121, v2
	v_mov_b32_e32 v122, v2
	v_mov_b32_e32 v123, v2
	v_mov_b32_e32 v124, v2
	v_mov_b32_e32 v125, v2
	v_mov_b32_e32 v126, v2
	v_mov_b32_e32 v127, v2
	v_mov_b32_e32 v128, v2
	v_mov_b32_e32 v129, v2
	s_branch .Lpeel329_330
.Lpeel329_330:
	s_cmp_lg_u32 s87, s1
	s_cselect_b64 s[64:65], -1, 0
	s_cmp_eq_u32 s87, s1
	s_mov_b64 s[68:69], s[2:3]
	s_cbranch_scc1 .Lpeel329_332
	s_add_u32 s68, s6, s42
	s_addc_u32 s69, s7, s43

; #define PG8_STAGE(bufoff, gbase, voff) do { _Pragma("unroll") for (int _i = 0; _i < 2; ++_i) \
;         __builtin_amdgcn_global_load_lds((const unsigned*)((const char*)(gbase) + (voff)[_i]), (LAS unsigned*)(lds + (bufoff) + ldsw + _i * 8192), 16, 0, 0); } while (0)
; #define PG8_LDA(dst, b, h) do { _Pragma("unroll") for (int m = 0; m < 4; ++m) _Pragma("unroll") for (int k = 0; k < 2; ++k) dst[m][k] = *(const LAS bf16x8*)(lds + PG8_SA(b, h) + aoff + m * 2048 + k * 1024); } while (0)
; #define PG8_LDB(dst, b, h) do { _Pragma("unroll") for (int n = 0; n < 2; ++n) _Pragma("unroll") for (int k = 0; k < 2; ++k) dst[n][k] = *(const LAS bf16x8*)(lds + PG8_SB(b, h) + boff + n * 2048 + k * 1024); } while (0)
; #define PG8_MMA(ai, bj, At, Bt) do { __builtin_amdgcn_s_setprio(1); _Pragma("unroll") for (int m = 0; m < 4; ++m) _Pragma("unroll") for (int n = 0; n < 2; ++n) _Pragma("unroll") for (int k = 0; k < 2; ++k) \
;         acc[ai][bj][m][n] = __builtin_amdgcn_mfma_f32_16x16x32_bf16(Bt[n][k], At[m][k], acc[ai][bj][m][n], 0, 0, 0); __builtin_amdgcn_s_setprio(0); } while (0)
; #define PG8_WAIT_V(n) asm volatile("s_waitcnt vmcnt(" #n ")" ::: "memory")
; #define PG8_WAIT_L(n) asm volatile("s_waitcnt lgkmcnt(" #n ")" ::: "memory")
; #define PG8_BAR __builtin_amdgcn_s_barrier()
; #define PG8_SCHED __builtin_amdgcn_sched_barrier(0)
; template <int MODE> __device__ __forceinline__ void gemm_phase(LAS unsigned char* lds, const GD& g, const int tid) {
;     ...
;         for (int t = 0; t < nt; t += 2) {
;             const bool last = (t == nt - 2);
;             const char* a1 = cA + (size_t)(t + 1) * kstA;
;             const char* a2 = last ? nA : cA + (size_t)(t + 2) * kstA; const char* b2 = last ? nB : cB + (size_t)(t + 2) * kstB;
;             const char* a3 = a2 + kstA; const char* b3 = b2 + kstB;
;             PG8_LDB(B0, 0, 0); PG8_LDB(B1, 0, 1); PG8_SCHED; PG8_LDA(At, 0, 0); PG8_STAGE(PG8_SA(1, 1), a1 + hsA, voffA);
;             PG8_WAIT_V(8); PG8_WAIT_L(0); PG8_BAR; PG8_MMA(0, 0, At, B0); PG8_MMA(0, 1, At, B1); PG8_BAR; PG8_SCHED;
;             PG8_LDA(At, 0, 1); PG8_STAGE(PG8_SB(0, 0), b2, voffB); PG8_STAGE(PG8_SB(0, 1), b2 + hsB, voffB); PG8_STAGE(PG8_SA(0, 0), a2, voffA);
;             PG8_WAIT_V(8); PG8_WAIT_L(0); PG8_BAR; PG8_MMA(1, 0, At, B0); PG8_MMA(1, 1, At, B1); PG8_BAR; PG8_SCHED;
.Lpeel329_329:
	s_add_i32 s1, s1, 2
	s_add_u32 vcc_lo, s68, s20
	s_addc_u32 vcc_hi, s69, s21
	s_add_i32 s11, 0, 0x10000
	v_add_u32_e32 v1, s11, v173
	s_add_i32 s14, 0, 0x14000
	ds_read_b128 v[146:149], v1
	ds_read_b128 v[150:153], v1 offset:1024
	ds_read_b128 v[154:157], v1 offset:2048
	ds_read_b128 v[158:161], v1 offset:3072
	v_add_u32_e32 v1, s14, v173
	ds_read_b128 v[184:187], v1
	ds_read_b128 v[188:191], v1 offset:1024
	ds_read_b128 v[196:199], v1 offset:2048
	ds_read_b128 v[204:207], v1 offset:3072
	v_lshl_add_u64 v[192:193], s[6:7], 0, v[144:145]
	s_add_i32 m0, s26, 0xc000
	ds_read_b128 v[220:223], v182
	ds_read_b128 v[224:227], v182 offset:1024
	ds_read_b128 v[228:231], v182 offset:2048
	ds_read_b128 v[232:235], v182 offset:3072
	ds_read_b128 v[236:239], v182 offset:4096
	ds_read_b128 v[240:243], v182 offset:5120
	ds_read_b128 v[244:247], v182 offset:6144
	ds_read_b128 v[248:251], v182 offset:7168
	global_load_lds_dwordx4 v[192:193], off
	v_lshl_add_u64 v[192:193], s[6:7], 0, v[142:143]
	s_add_i32 m0, s26, 0xe000
	s_nop 0
	global_load_lds_dwordx4 v[192:193], off
	s_waitcnt vmcnt(16)
	s_waitcnt lgkmcnt(0)
	s_barrier
	s_setprio 1
	s_waitcnt lgkmcnt(0)
	v_mfma_f32_16x16x32_bf16 v[126:129], v[146:149], v[220:223], v[126:129]
	v_mfma_f32_16x16x32_bf16 v[122:125], v[154:157], v[220:223], v[122:125]
	v_mfma_f32_16x16x32_bf16 v[118:121], v[146:149], v[228:231], v[118:121]
	v_mfma_f32_16x16x32_bf16 v[110:113], v[154:157], v[228:231], v[110:113]
	v_mfma_f32_16x16x32_bf16 v[102:105], v[146:149], v[236:239], v[102:105]
	v_mfma_f32_16x16x32_bf16 v[94:97], v[154:157], v[236:239], v[94:97]
	v_mfma_f32_16x16x32_bf16 v[86:89], v[146:149], v[244:247], v[86:89]
	v_mfma_f32_16x16x32_bf16 v[78:81], v[154:157], v[244:247], v[78:81]
	v_mfma_f32_16x16x32_bf16 v[126:129], v[150:153], v[224:227], v[126:129]
	v_mfma_f32_16x16x32_bf16 v[122:125], v[158:161], v[224:227], v[122:125]
	v_mfma_f32_16x16x32_bf16 v[118:121], v[150:153], v[232:235], v[118:121]
	v_mfma_f32_16x16x32_bf16 v[110:113], v[158:161], v[232:235], v[110:113]
	v_mfma_f32_16x16x32_bf16 v[102:105], v[150:153], v[240:243], v[102:105]
	v_mfma_f32_16x16x32_bf16 v[94:97], v[158:161], v[240:243], v[94:97]
	v_mfma_f32_16x16x32_bf16 v[86:89], v[150:153], v[248:251], v[86:89]
	v_mfma_f32_16x16x32_bf16 v[78:81], v[158:161], v[248:251], v[78:81]
	s_setprio 0
	s_setprio 1
	v_mfma_f32_16x16x32_bf16 v[114:117], v[184:187], v[220:223], v[114:117]
	v_mfma_f32_16x16x32_bf16 v[106:109], v[196:199], v[220:223], v[106:109]
	v_mfma_f32_16x16x32_bf16 v[98:101], v[184:187], v[228:231], v[98:101]
	v_mfma_f32_16x16x32_bf16 v[90:93], v[196:199], v[228:231], v[90:93]
	v_mfma_f32_16x16x32_bf16 v[82:85], v[184:187], v[236:239], v[82:85]
	v_mfma_f32_16x16x32_bf16 v[74:77], v[196:199], v[236:239], v[74:77]
	v_mfma_f32_16x16x32_bf16 v[70:73], v[184:187], v[244:247], v[70:73]
	v_mfma_f32_16x16x32_bf16 v[66:69], v[196:199], v[244:247], v[66:69]
	v_mfma_f32_16x16x32_bf16 v[114:117], v[188:191], v[224:227], v[114:117]
	v_mfma_f32_16x16x32_bf16 v[106:109], v[204:207], v[224:227], v[106:109]
	v_mfma_f32_16x16x32_bf16 v[98:101], v[188:191], v[232:235], v[98:101]
	v_mfma_f32_16x16x32_bf16 v[90:93], v[204:207], v[232:235], v[90:93]
	v_mfma_f32_16x16x32_bf16 v[82:85], v[188:191], v[240:243], v[82:85]
	v_mfma_f32_16x16x32_bf16 v[74:77], v[204:207], v[240:243], v[74:77]
	v_mfma_f32_16x16x32_bf16 v[70:73], v[188:191], v[248:251], v[70:73]
	v_mfma_f32_16x16x32_bf16 v[66:69], v[204:207], v[248:251], v[66:69]
	s_setprio 0
	s_barrier
	s_add_i32 s11, s11, s25
	v_lshl_add_u64 v[192:193], s[64:65], 0, v[132:133]
	s_mov_b32 m0, s11
	ds_read_b128 v[220:223], v182 offset:16384
	ds_read_b128 v[224:227], v182 offset:17408
	ds_read_b128 v[228:231], v182 offset:18432
	ds_read_b128 v[232:235], v182 offset:19456
	ds_read_b128 v[236:239], v182 offset:20480
	ds_read_b128 v[240:243], v182 offset:21504
	ds_read_b128 v[244:247], v182 offset:22528
	ds_read_b128 v[248:251], v182 offset:23552
	global_load_lds_dwordx4 v[192:193], off
	s_add_i32 m0, s11, 0x2000
	s_add_u32 s12, s64, s58
	v_lshl_add_u64 v[192:193], s[64:65], 0, v[136:137]
	s_addc_u32 s13, s65, s59
	s_add_i32 s11, s14, s25
	global_load_lds_dwordx4 v[192:193], off
	v_lshl_add_u64 v[192:193], s[12:13], 0, v[132:133]
	s_mov_b32 m0, s11
	s_nop 0
	global_load_lds_dwordx4 v[192:193], off
	v_lshl_add_u64 v[192:193], s[12:13], 0, v[136:137]
	s_add_i32 m0, s11, 0x2000
	s_nop 0
	global_load_lds_dwordx4 v[192:193], off
	v_lshl_add_u64 v[192:193], s[68:69], 0, v[130:131]
	s_mov_b32 m0, s26
	s_nop 0
	global_load_lds_dwordx4 v[192:193], off
	v_lshl_add_u64 v[192:193], s[68:69], 0, v[134:135]
	s_mov_b32 m0, s27
	s_nop 0
	global_load_lds_dwordx4 v[192:193], off
	s_waitcnt vmcnt(16)
	s_waitcnt lgkmcnt(0)
	s_barrier
; #define PG8_STAGE(bufoff, gbase, voff) do { _Pragma("unroll") for (int _i = 0; _i < 2; ++_i) \
;         __builtin_amdgcn_global_load_lds((const unsigned*)((const char*)(gbase) + (voff)[_i]), (LAS unsigned*)(lds + (bufoff) + ldsw + _i * 8192), 16, 0, 0); } while (0)
; #define PG8_LDA(dst, b, h) do { _Pragma("unroll") for (int m = 0; m < 4; ++m) _Pragma("unroll") for (int k = 0; k < 2; ++k) dst[m][k] = *(const LAS bf16x8*)(lds + PG8_SA(b, h) + aoff + m * 2048 + k * 1024); } while (0)
; #define PG8_LDB(dst, b, h) do { _Pragma("unroll") for (int n = 0; n < 2; ++n) _Pragma("unroll") for (int k = 0; k < 2; ++k) dst[n][k] = *(const LAS bf16x8*)(lds + PG8_SB(b, h) + boff + n * 2048 + k * 1024); } while (0)
; #define PG8_MMA(ai, bj, At, Bt) do { __builtin_amdgcn_s_setprio(1); _Pragma("unroll") for (int m = 0; m < 4; ++m) _Pragma("unroll") for (int n = 0; n < 2; ++n) _Pragma("unroll") for (int k = 0; k < 2; ++k) \
;         acc[ai][bj][m][n] = __builtin_amdgcn_mfma_f32_16x16x32_bf16(Bt[n][k], At[m][k], acc[ai][bj][m][n], 0, 0, 0); __builtin_amdgcn_s_setprio(0); } while (0)
; #define PG8_WAIT_V(n) asm volatile("s_waitcnt vmcnt(" #n ")" ::: "memory")
; #define PG8_WAIT_L(n) asm volatile("s_waitcnt lgkmcnt(" #n ")" ::: "memory")
; #define PG8_BAR __builtin_amdgcn_s_barrier()
; #define PG8_SCHED __builtin_amdgcn_sched_barrier(0)
; template <int MODE> __device__ __forceinline__ void gemm_phase(LAS unsigned char* lds, const GD& g, const int tid) {
;     ...
;             PG8_WAIT_V(8); PG8_WAIT_L(0); PG8_BAR; PG8_MMA(1, 0, At, B0); PG8_MMA(1, 1, At, B1); PG8_BAR; PG8_SCHED;
;             PG8_LDB(B0, 1, 0); PG8_LDB(B1, 1, 1); PG8_SCHED; PG8_LDA(At, 1, 0); PG8_STAGE(PG8_SA(0, 1), a2 + hsA, voffA);
;             PG8_WAIT_V(8); PG8_WAIT_L(0); PG8_BAR; PG8_MMA(0, 0, At, B0); PG8_MMA(0, 1, At, B1); PG8_BAR; PG8_SCHED;
	s_setprio 1
	s_waitcnt lgkmcnt(0)
	v_mfma_f32_16x16x32_bf16 v[62:65], v[146:149], v[220:223], v[62:65]
	v_mfma_f32_16x16x32_bf16 v[58:61], v[154:157], v[220:223], v[58:61]
	v_mfma_f32_16x16x32_bf16 v[54:57], v[146:149], v[228:231], v[54:57]
	v_mfma_f32_16x16x32_bf16 v[46:49], v[154:157], v[228:231], v[46:49]
	v_mfma_f32_16x16x32_bf16 v[38:41], v[146:149], v[236:239], v[38:41]
	v_mfma_f32_16x16x32_bf16 v[30:33], v[154:157], v[236:239], v[30:33]
	v_mfma_f32_16x16x32_bf16 v[22:25], v[146:149], v[244:247], v[22:25]
	v_mfma_f32_16x16x32_bf16 v[14:17], v[154:157], v[244:247], v[14:17]
	v_mfma_f32_16x16x32_bf16 v[62:65], v[150:153], v[224:227], v[62:65]
	v_mfma_f32_16x16x32_bf16 v[58:61], v[158:161], v[224:227], v[58:61]
	v_mfma_f32_16x16x32_bf16 v[54:57], v[150:153], v[232:235], v[54:57]
	v_mfma_f32_16x16x32_bf16 v[46:49], v[158:161], v[232:235], v[46:49]
	v_mfma_f32_16x16x32_bf16 v[38:41], v[150:153], v[240:243], v[38:41]
	v_mfma_f32_16x16x32_bf16 v[30:33], v[158:161], v[240:243], v[30:33]
	v_mfma_f32_16x16x32_bf16 v[22:25], v[150:153], v[248:251], v[22:25]
	v_mfma_f32_16x16x32_bf16 v[14:17], v[158:161], v[248:251], v[14:17]
	s_setprio 0
	s_setprio 1
	v_mfma_f32_16x16x32_bf16 v[50:53], v[184:187], v[220:223], v[50:53]
	v_mfma_f32_16x16x32_bf16 v[42:45], v[196:199], v[220:223], v[42:45]
	v_mfma_f32_16x16x32_bf16 v[34:37], v[184:187], v[228:231], v[34:37]
	v_mfma_f32_16x16x32_bf16 v[26:29], v[196:199], v[228:231], v[26:29]
	v_mfma_f32_16x16x32_bf16 v[18:21], v[184:187], v[236:239], v[18:21]
	v_mfma_f32_16x16x32_bf16 v[10:13], v[196:199], v[236:239], v[10:13]
	v_mfma_f32_16x16x32_bf16 v[6:9], v[184:187], v[244:247], v[6:9]
	v_mfma_f32_16x16x32_bf16 v[2:5], v[196:199], v[244:247], v[2:5]
	v_mfma_f32_16x16x32_bf16 v[50:53], v[188:191], v[224:227], v[50:53]
	v_mfma_f32_16x16x32_bf16 v[42:45], v[204:207], v[224:227], v[42:45]
	v_mfma_f32_16x16x32_bf16 v[34:37], v[188:191], v[232:235], v[34:37]
	v_mfma_f32_16x16x32_bf16 v[26:29], v[204:207], v[232:235], v[26:29]
	v_mfma_f32_16x16x32_bf16 v[18:21], v[188:191], v[240:243], v[18:21]
	v_mfma_f32_16x16x32_bf16 v[10:13], v[204:207], v[240:243], v[10:13]
	v_mfma_f32_16x16x32_bf16 v[6:9], v[188:191], v[248:251], v[6:9]
	v_mfma_f32_16x16x32_bf16 v[2:5], v[204:207], v[248:251], v[2:5]
	s_setprio 0
	s_barrier
	s_add_i32 s11, 0, 0x18000
	v_add_u32_e32 v1, s11, v173
	s_add_i32 s14, 0, 0x1c000
	ds_read_b128 v[146:149], v1
	ds_read_b128 v[150:153], v1 offset:1024
	ds_read_b128 v[154:157], v1 offset:2048
	ds_read_b128 v[158:161], v1 offset:3072
	v_add_u32_e32 v1, s14, v173
	ds_read_b128 v[184:187], v1
	ds_read_b128 v[188:191], v1 offset:1024
	ds_read_b128 v[196:199], v1 offset:2048
	ds_read_b128 v[204:207], v1 offset:3072
	s_add_u32 s12, s68, s46
	s_addc_u32 s13, s69, s47
	s_mov_b32 m0, s28
	v_lshl_add_u64 v[192:193], s[12:13], 0, v[130:131]
	ds_read_b128 v[220:223], v182 offset:32768
	ds_read_b128 v[224:227], v182 offset:33792
	ds_read_b128 v[228:231], v182 offset:34816
	ds_read_b128 v[232:235], v182 offset:35840
	ds_read_b128 v[236:239], v182 offset:36864
	ds_read_b128 v[240:243], v182 offset:37888
	ds_read_b128 v[244:247], v182 offset:38912
	ds_read_b128 v[248:251], v182 offset:39936
	global_load_lds_dwordx4 v[192:193], off
	v_lshl_add_u64 v[192:193], s[12:13], 0, v[134:135]
	s_mov_b32 m0, s29
	s_nop 0
	global_load_lds_dwordx4 v[192:193], off
	s_waitcnt vmcnt(8)
	s_waitcnt lgkmcnt(0)
	s_barrier
	s_setprio 1
	s_waitcnt lgkmcnt(0)
	v_mfma_f32_16x16x32_bf16 v[126:129], v[146:149], v[220:223], v[126:129]
	v_mfma_f32_16x16x32_bf16 v[122:125], v[154:157], v[220:223], v[122:125]
	v_mfma_f32_16x16x32_bf16 v[118:121], v[146:149], v[228:231], v[118:121]
	v_mfma_f32_16x16x32_bf16 v[110:113], v[154:157], v[228:231], v[110:113]
	v_mfma_f32_16x16x32_bf16 v[102:105], v[146:149], v[236:239], v[102:105]
	v_mfma_f32_16x16x32_bf16 v[94:97], v[154:157], v[236:239], v[94:97]
	v_mfma_f32_16x16x32_bf16 v[86:89], v[146:149], v[244:247], v[86:89]
	v_mfma_f32_16x16x32_bf16 v[78:81], v[154:157], v[244:247], v[78:81]
	v_mfma_f32_16x16x32_bf16 v[126:129], v[150:153], v[224:227], v[126:129]
	v_mfma_f32_16x16x32_bf16 v[122:125], v[158:161], v[224:227], v[122:125]
	v_mfma_f32_16x16x32_bf16 v[118:121], v[150:153], v[232:235], v[118:121]
	v_mfma_f32_16x16x32_bf16 v[110:113], v[158:161], v[232:235], v[110:113]
	v_mfma_f32_16x16x32_bf16 v[102:105], v[150:153], v[240:243], v[102:105]
	v_mfma_f32_16x16x32_bf16 v[94:97], v[158:161], v[240:243], v[94:97]
	v_mfma_f32_16x16x32_bf16 v[86:89], v[150:153], v[248:251], v[86:89]
	v_mfma_f32_16x16x32_bf16 v[78:81], v[158:161], v[248:251], v[78:81]
	s_setprio 0
	s_setprio 1
	v_mfma_f32_16x16x32_bf16 v[114:117], v[184:187], v[220:223], v[114:117]
	v_mfma_f32_16x16x32_bf16 v[106:109], v[196:199], v[220:223], v[106:109]
	v_mfma_f32_16x16x32_bf16 v[98:101], v[184:187], v[228:231], v[98:101]
	v_mfma_f32_16x16x32_bf16 v[90:93], v[196:199], v[228:231], v[90:93]
	v_mfma_f32_16x16x32_bf16 v[82:85], v[184:187], v[236:239], v[82:85]
	v_mfma_f32_16x16x32_bf16 v[74:77], v[196:199], v[236:239], v[74:77]
	v_mfma_f32_16x16x32_bf16 v[70:73], v[184:187], v[244:247], v[70:73]
	v_mfma_f32_16x16x32_bf16 v[66:69], v[196:199], v[244:247], v[66:69]
	v_mfma_f32_16x16x32_bf16 v[114:117], v[188:191], v[224:227], v[114:117]
	v_mfma_f32_16x16x32_bf16 v[106:109], v[204:207], v[224:227], v[106:109]
	v_mfma_f32_16x16x32_bf16 v[98:101], v[188:191], v[232:235], v[98:101]
	v_mfma_f32_16x16x32_bf16 v[90:93], v[204:207], v[232:235], v[90:93]
	v_mfma_f32_16x16x32_bf16 v[82:85], v[188:191], v[240:243], v[82:85]
	v_mfma_f32_16x16x32_bf16 v[74:77], v[204:207], v[240:243], v[74:77]
	v_mfma_f32_16x16x32_bf16 v[70:73], v[188:191], v[248:251], v[70:73]
	v_mfma_f32_16x16x32_bf16 v[66:69], v[204:207], v[248:251], v[66:69]
	s_setprio 0
	s_barrier
; #define PG8_STAGE(bufoff, gbase, voff) do { _Pragma("unroll") for (int _i = 0; _i < 2; ++_i) \
;         __builtin_amdgcn_global_load_lds((const unsigned*)((const char*)(gbase) + (voff)[_i]), (LAS unsigned*)(lds + (bufoff) + ldsw + _i * 8192), 16, 0, 0); } while (0)
; #define PG8_LDA(dst, b, h) do { _Pragma("unroll") for (int m = 0; m < 4; ++m) _Pragma("unroll") for (int k = 0; k < 2; ++k) dst[m][k] = *(const LAS bf16x8*)(lds + PG8_SA(b, h) + aoff + m * 2048 + k * 1024); } while (0)
; #define PG8_MMA(ai, bj, At, Bt) do { __builtin_amdgcn_s_setprio(1); _Pragma("unroll") for (int m = 0; m < 4; ++m) _Pragma("unroll") for (int n = 0; n < 2; ++n) _Pragma("unroll") for (int k = 0; k < 2; ++k) \
;         acc[ai][bj][m][n] = __builtin_amdgcn_mfma_f32_16x16x32_bf16(Bt[n][k], At[m][k], acc[ai][bj][m][n], 0, 0, 0); __builtin_amdgcn_s_setprio(0); } while (0)
; #define PG8_WAIT_V(n) asm volatile("s_waitcnt vmcnt(" #n ")" ::: "memory")
; #define PG8_WAIT_L(n) asm volatile("s_waitcnt lgkmcnt(" #n ")" ::: "memory")
; #define PG8_BAR __builtin_amdgcn_s_barrier()
; #define PG8_SCHED __builtin_amdgcn_sched_barrier(0)
; template <int MODE> __device__ __forceinline__ void gemm_phase(LAS unsigned char* lds, const GD& g, const int tid) {
;     ...
;             PG8_LDA(At, 1, 1); PG8_STAGE(PG8_SB(1, 0), b3, voffB); PG8_STAGE(PG8_SB(1, 1), b3 + hsB, voffB); PG8_STAGE(PG8_SA(1, 0), a3, voffA);
;             PG8_WAIT_V(8); PG8_WAIT_L(0); PG8_BAR; PG8_MMA(1, 0, At, B0); PG8_MMA(1, 1, At, B1); PG8_BAR; PG8_SCHED;
;         }
	s_add_u32 s12, s64, s22
	s_addc_u32 s13, s65, s23
	s_add_i32 s11, s11, s25
	v_lshl_add_u64 v[192:193], s[12:13], 0, v[132:133]
	s_mov_b32 m0, s11
	ds_read_b128 v[220:223], v182 offset:49152
	ds_read_b128 v[224:227], v182 offset:50176
	ds_read_b128 v[228:231], v182 offset:51200
	ds_read_b128 v[232:235], v182 offset:52224
	ds_read_b128 v[236:239], v182 offset:53248
	ds_read_b128 v[240:243], v182 offset:54272
	ds_read_b128 v[244:247], v182 offset:55296
	ds_read_b128 v[248:251], v182 offset:56320
	global_load_lds_dwordx4 v[192:193], off
	s_add_i32 m0, s11, 0x2000
	v_lshl_add_u64 v[192:193], s[12:13], 0, v[136:137]
	s_add_u32 s12, s12, s58
	s_addc_u32 s13, s13, s59
	s_add_i32 s11, s14, s25
	global_load_lds_dwordx4 v[192:193], off
	v_lshl_add_u64 v[192:193], s[12:13], 0, v[132:133]
	s_mov_b32 m0, s11
	s_nop 0
	global_load_lds_dwordx4 v[192:193], off
	v_lshl_add_u64 v[192:193], s[12:13], 0, v[136:137]
	s_add_i32 m0, s11, 0x2000
	s_nop 0
	global_load_lds_dwordx4 v[192:193], off
	v_lshl_add_u64 v[192:193], vcc, 0, v[130:131]
	s_mov_b32 m0, s93
	s_nop 0
	global_load_lds_dwordx4 v[192:193], off
	v_lshl_add_u64 v[192:193], vcc, 0, v[134:135]
	s_mov_b32 m0, s86
	s_nop 0
	global_load_lds_dwordx4 v[192:193], off
	s_waitcnt vmcnt(8)
	s_waitcnt lgkmcnt(0)
	s_barrier
	s_setprio 1
	s_waitcnt lgkmcnt(0)
	v_mfma_f32_16x16x32_bf16 v[62:65], v[146:149], v[220:223], v[62:65]
	v_mfma_f32_16x16x32_bf16 v[58:61], v[154:157], v[220:223], v[58:61]
	v_mfma_f32_16x16x32_bf16 v[54:57], v[146:149], v[228:231], v[54:57]
	v_mfma_f32_16x16x32_bf16 v[46:49], v[154:157], v[228:231], v[46:49]
	v_mfma_f32_16x16x32_bf16 v[38:41], v[146:149], v[236:239], v[38:41]
	v_mfma_f32_16x16x32_bf16 v[30:33], v[154:157], v[236:239], v[30:33]
	v_mfma_f32_16x16x32_bf16 v[22:25], v[146:149], v[244:247], v[22:25]
	v_mfma_f32_16x16x32_bf16 v[14:17], v[154:157], v[244:247], v[14:17]
	v_mfma_f32_16x16x32_bf16 v[62:65], v[150:153], v[224:227], v[62:65]
	v_mfma_f32_16x16x32_bf16 v[58:61], v[158:161], v[224:227], v[58:61]
	v_mfma_f32_16x16x32_bf16 v[54:57], v[150:153], v[232:235], v[54:57]
	v_mfma_f32_16x16x32_bf16 v[46:49], v[158:161], v[232:235], v[46:49]
	v_mfma_f32_16x16x32_bf16 v[38:41], v[150:153], v[240:243], v[38:41]
	v_mfma_f32_16x16x32_bf16 v[30:33], v[158:161], v[240:243], v[30:33]
	v_mfma_f32_16x16x32_bf16 v[22:25], v[150:153], v[248:251], v[22:25]
	v_mfma_f32_16x16x32_bf16 v[14:17], v[158:161], v[248:251], v[14:17]
	s_setprio 0
	s_setprio 1
	v_mfma_f32_16x16x32_bf16 v[50:53], v[184:187], v[220:223], v[50:53]
	v_mfma_f32_16x16x32_bf16 v[42:45], v[196:199], v[220:223], v[42:45]
	v_mfma_f32_16x16x32_bf16 v[34:37], v[184:187], v[228:231], v[34:37]
	v_mfma_f32_16x16x32_bf16 v[26:29], v[196:199], v[228:231], v[26:29]
	v_mfma_f32_16x16x32_bf16 v[18:21], v[184:187], v[236:239], v[18:21]
	v_mfma_f32_16x16x32_bf16 v[10:13], v[196:199], v[236:239], v[10:13]
	v_mfma_f32_16x16x32_bf16 v[6:9], v[184:187], v[244:247], v[6:9]
	v_mfma_f32_16x16x32_bf16 v[2:5], v[196:199], v[244:247], v[2:5]
	v_mfma_f32_16x16x32_bf16 v[50:53], v[188:191], v[224:227], v[50:53]
	v_mfma_f32_16x16x32_bf16 v[42:45], v[204:207], v[224:227], v[42:45]
	v_mfma_f32_16x16x32_bf16 v[34:37], v[188:191], v[232:235], v[34:37]
	v_mfma_f32_16x16x32_bf16 v[26:29], v[204:207], v[232:235], v[26:29]
	v_mfma_f32_16x16x32_bf16 v[18:21], v[188:191], v[240:243], v[18:21]
	v_mfma_f32_16x16x32_bf16 v[10:13], v[204:207], v[240:243], v[10:13]
	v_mfma_f32_16x16x32_bf16 v[6:9], v[188:191], v[248:251], v[6:9]
	v_mfma_f32_16x16x32_bf16 v[2:5], v[204:207], v[248:251], v[2:5]
	s_setprio 0
	s_barrier
	s_add_u32 s8, s8, s94
	s_addc_u32 s9, s9, s95
	s_add_u32 s6, s6, s42
	s_addc_u32 s7, s7, s43
	s_cmp_ge_i32 s1, s92
	s_cbranch_scc1 .LBB0_335
	s_branch .LBB0_330

; #define PG8_STAGE(bufoff, gbase, voff) do { _Pragma("unroll") for (int _i = 0; _i < 2; ++_i) \
;         __builtin_amdgcn_global_load_lds((const unsigned*)((const char*)(gbase) + (voff)[_i]), (LAS unsigned*)(lds + (bufoff) + ldsw + _i * 8192), 16, 0, 0); } while (0)
; #define PG8_WAIT_V(n) asm volatile("s_waitcnt vmcnt(" #n ")" ::: "memory")
; #define PG8_BAR __builtin_amdgcn_s_barrier()
; template <int MODE> __device__ __forceinline__ void gemm_phase(LAS unsigned char* lds, const GD& g, const int tid) {
;     ...
;     PG8_STAGE(PG8_SB(0, 0), cB, voffB); PG8_STAGE(PG8_SB(0, 1), cB + hsB, voffB); PG8_STAGE(PG8_SA(0, 0), cA, voffA); PG8_STAGE(PG8_SA(0, 1), cA + hsA, voffA);
;     if (wr == 1) PG8_BAR;
;     PG8_WAIT_V(2); PG8_BAR;
;     PG8_STAGE(PG8_SB(1, 0), cB + kstB, voffB); PG8_STAGE(PG8_SA(1, 0), cA + kstA, voffA); PG8_STAGE(PG8_SB(1, 1), cB + hsB + kstB, voffB);
;     PG8_WAIT_V(6); PG8_BAR;
;     for (;;) {
;         const bool has_next = gd_next(g, ui + 1, nxt);
.LBB0_378:
	s_ashr_i32 s9, s56, 31
	s_lshr_b32 s9, s9, 26
	v_lshrrev_b32_e32 v8, 1, v194
	s_add_i32 s9, s56, s9
	v_and_b32_e32 v10, 24, v8
	s_ashr_i32 s36, s9, 6
	v_lshlrev_b32_e32 v8, 6, v164
	v_lshlrev_b32_e32 v9, 1, v10
	s_movk_i32 s9, 0x3c0
	s_lshl_b32 s4, s4, 5
	v_and_or_b32 v8, v8, s9, v9
	s_and_b32 s9, s4, 0x60
	s_ashr_i32 s21, s20, 31
	s_ashr_i32 s23, s22, 31
	s_lshl_b32 s5, s5, 13
	v_lshlrev_b32_e32 v11, 2, v164
	s_lshl_b32 s10, s9, 7
	v_and_b32_e32 v11, 32, v11
	s_add_u32 s4, s42, s22
	v_mov_b32_e32 v149, v0
	v_bitop3_b32 v11, v8, s5, v11 bitop3:0xde
	s_addc_u32 s5, s43, s23
	v_lshl_or_b32 v12, v7, 6, v9
	s_add_i32 m0, s27, 0x18000
	v_lshl_add_u64 v[8:9], s[4:5], 0, v[148:149]
	v_mov_b32_e32 v153, v0
	s_waitcnt vmcnt(2)
	s_barrier
	global_load_lds_dwordx4 v[8:9], off
	s_add_i32 m0, s27, 0x1a000
	v_lshl_add_u64 v[8:9], s[4:5], 0, v[152:153]
	s_add_u32 s4, s6, s20
	v_mov_b32_e32 v147, v0
	s_addc_u32 s5, s7, s21
	s_add_i32 s82, s27, 0x8000
	s_add_i32 s83, s27, 0xa000
	v_mov_b32_e32 v151, v0
	global_load_lds_dwordx4 v[8:9], off
	v_lshl_add_u64 v[8:9], s[4:5], 0, v[146:147]
	s_mov_b32 m0, s82
	s_add_u32 s2, s2, s22
	global_load_lds_dwordx4 v[8:9], off
	v_lshl_add_u64 v[8:9], s[4:5], 0, v[150:151]
	s_mov_b32 m0, s83
	s_addc_u32 s3, s3, s23
	global_load_lds_dwordx4 v[8:9], off
	s_add_i32 m0, s27, 0x1c000
	v_lshl_add_u64 v[8:9], s[2:3], 0, v[148:149]
	global_load_lds_dwordx4 v[8:9], off
	s_add_i32 m0, s27, 0x1e000
	s_cmp_gt_i32 s56, 63
	s_cselect_b64 s[94:95], -1, 0
	s_add_i32 s69, s36, -2
	v_lshl_add_u64 v[8:9], s[2:3], 0, v[152:153]
	s_cmpk_lt_u32 s8, 0x100
	v_readlane_b32 s11, v254, 33
	v_readlane_b32 s2, v254, 60
	s_cselect_b64 s[60:61], -1, 0
	s_mul_i32 s81, s59, s11
	s_cmp_lg_u32 s2, 1
	s_mul_i32 s33, s2, s81
	s_cselect_b64 s[2:3], -1, 0
	v_writelane_b32 v255, s2, 6
	s_cmp_eq_u32 s11, 16
	global_load_lds_dwordx4 v[8:9], off
	v_writelane_b32 v255, s3, 7
	s_cselect_b64 s[2:3], -1, 0
	s_and_b32 s4, s59, 3
	s_cmp_eq_u32 s4, 0
	s_cselect_b64 s[4:5], -1, 0
	s_and_b64 s[2:3], s[2:3], s[4:5]
	s_and_b32 s4, s52, 7
	s_cmp_eq_u32 s4, 0
	s_cselect_b64 s[4:5], -1, 0
	s_and_b64 s[2:3], s[2:3], s[4:5]
	s_mov_b64 s[28:29], s[2:3]
	s_xor_b64 s[2:3], s[2:3], -1
	v_writelane_b32 v255, s2, 16
	s_lshl_b32 s12, s59, 3
	v_lshlrev_b32_e32 v7, 2, v7
	v_writelane_b32 v255, s3, 17
	s_and_b32 s2, s53, 7
	s_ashr_i32 s3, s52, 3
	s_mul_i32 s2, s3, s2
	s_lshr_b32 s3, s53, 3
	s_add_i32 s2, s2, s3
	s_abs_i32 s3, s52
	v_cvt_f32_u32_e32 v8, s3
	v_writelane_b32 v255, s2, 23
	s_ashr_i32 s2, s81, 31
	s_mov_b32 s35, s2
	v_rcp_iflag_f32_e32 v8, v8
	s_lshr_b32 s2, s2, 29
	s_sub_i32 s5, 0, s3
	s_add_i32 s2, s81, s2
	v_mul_f32_e32 v8, 0x4f7ffffe, v8
	v_cvt_u32_f32_e32 v8, v8
	s_ashr_i32 s4, s2, 3
	s_and_b32 s2, s2, -8
	s_sub_i32 s38, s81, s2
	v_readfirstlane_b32 s8, v8
	s_mul_i32 s5, s5, s8
	s_mul_hi_u32 s5, s8, s5
	v_writelane_b32 v255, s4, 24
	s_add_i32 s2, s4, 1
	s_abs_i32 s4, s33
	s_add_i32 s8, s8, s5
	s_mul_hi_u32 s5, s4, s8
	s_mul_i32 s5, s5, s3
	s_sub_i32 s4, s4, s5
	v_writelane_b32 v255, s2, 20
	s_ashr_i32 s2, s33, 31
	s_sub_i32 s5, s4, s3
	s_cmp_ge_u32 s4, s3
	s_cselect_b32 s4, s5, s4
	s_sub_i32 s5, s4, s3
	s_cmp_ge_u32 s4, s3
	s_cselect_b32 s3, s5, s4
	s_xor_b32 s3, s3, s2
	s_sub_i32 s2, s3, s2
	s_cmp_lg_u32 s2, 0
	s_cselect_b64 s[2:3], -1, 0
	s_abs_i32 s63, s81
	v_cvt_f32_u32_e32 v8, s63
	v_and_b32_e32 v7, 32, v7
	v_bitop3_b32 v173, s10, v12, v7 bitop3:0xf6
	s_abs_i32 s4, s11
	v_rcp_iflag_f32_e32 v7, v8
	v_cvt_f32_u32_e32 v8, s4
	v_writelane_b32 v255, s59, 9
	v_writelane_b32 v255, s2, 25
	v_mul_f32_e32 v7, 0x4f7ffffe, v7
	v_cvt_u32_f32_e32 v7, v7
	v_writelane_b32 v255, s3, 26
	s_sub_i32 s2, 0, s63
	s_abs_i32 s37, s12
	v_readfirstlane_b32 s3, v7
	v_rcp_iflag_f32_e32 v7, v8
	s_mul_i32 s2, s2, s3
	s_mul_hi_u32 s2, s3, s2
	s_add_i32 s2, s3, s2
	v_mul_f32_e32 v7, 0x4f7ffffe, v7
	v_cvt_u32_f32_e32 v7, v7
	v_cvt_f32_u32_e32 v8, s37
	v_writelane_b32 v255, s2, 4
	s_ashr_i32 s2, s11, 31
	v_writelane_b32 v255, s2, 27
	v_writelane_b32 v255, s4, 28
	s_sub_i32 s2, 0, s4
	v_readlane_b32 s4, v254, 58
	v_readfirstlane_b32 s3, v7
	v_rcp_iflag_f32_e32 v7, v8
	s_abs_i32 s30, s4
	v_cvt_f32_u32_e32 v8, s30
	s_mul_i32 s2, s2, s3
	v_mul_f32_e32 v7, 0x4f7ffffe, v7
	v_cvt_u32_f32_e32 v7, v7
	v_rcp_iflag_f32_e32 v8, v8
	s_mul_hi_u32 s2, s3, s2
	s_add_i32 s2, s3, s2
	v_writelane_b32 v255, s2, 30
	s_ashr_i32 s2, s12, 31
	v_writelane_b32 v255, s2, 8
	s_sub_i32 s2, 0, s37
	v_readfirstlane_b32 s3, v7
	v_mul_f32_e32 v7, 0x4f7ffffe, v8
	s_mul_i32 s2, s2, s3
	v_cvt_u32_f32_e32 v175, v7
	s_mul_hi_u32 s2, s3, s2
	s_add_i32 s2, s3, s2
	v_writelane_b32 v255, s2, 31
	s_ashr_i32 s2, s4, 31
	v_writelane_b32 v254, s2, 63
	s_sub_i32 s3, 0, s30
	v_readfirstlane_b32 s2, v175
	s_mov_b32 s18, s3
	s_mul_i32 s3, s3, s2
	s_mul_hi_u32 s3, s2, s3
	s_add_i32 s2, s2, s3
	s_lshl_b64 s[4:5], s[22:23], 1
	s_lshl_b64 s[44:45], s[20:21], 1
	s_waitcnt vmcnt(0)
	v_writelane_b32 v255, s2, 2
	s_add_u32 s2, s76, s20
	v_add_u32_e32 v4, v6, v4
	v_add_u32_e32 v1, v3, v1
	s_addc_u32 s3, s77, s21
	v_add_lshl_u32 v4, v4, v5, 1
	v_mov_b32_e32 v5, v0
	v_add_lshl_u32 v2, v1, v2, 1
	v_mov_b32_e32 v3, v0
	s_mov_b32 s62, 0
	v_or_b32_e32 v174, s9, v10
	s_mov_b32 s24, s12
	v_lshl_add_u64 v[154:155], s[2:3], 0, v[4:5]
	v_lshl_add_u64 v[156:157], s[2:3], 0, v[2:3]
	v_add_u32_e32 v176, 0, v11
	s_barrier
	s_branch .LBB0_381

; template <int MODE> __device__ __forceinline__ void gemm_phase(LAS unsigned char* lds, const GD& g, const int tid) {
;     ...
;         for (int t = 0; t < nt; t += 2) {
;             const bool last = (t == nt - 2);
;             const char* a1 = cA + (size_t)(t + 1) * kstA;
;             const char* a2 = last ? nA : cA + (size_t)(t + 2) * kstA; const char* b2 = last ? nB : cB + (size_t)(t + 2) * kstB;
;     ...
;         if (!has_next) break;
; #pragma unroll
;         for (int a = 0; a < 2; ++a)
; #pragma unroll
;             for (int b = 0; b < 2; ++b)
; #pragma unroll
;                 for (int m = 0; m < 4; ++m)
; #pragma unroll
;                     for (int n = 0; n < 2; ++n) acc[a][b][m][n] = (f32x4){0.f, 0.f, 0.f, 0.f};
;         cur = nxt; cA = nA; cB = nB; ++ui; rsv_load(rsv, g, cur, wr, fr);
.LBB0_398:
	s_andn2_b64 vcc, exec, s[94:95]
	s_cbranch_vccnz .LBB0_405
	s_and_b64 s[2:3], s[86:87], exec
	s_cselect_b32 s9, s59, s7
	s_cselect_b32 s8, s58, s6
	s_cselect_b32 s11, s47, s43
	s_cselect_b32 s10, s46, s42
	s_add_u32 s42, s42, s4
	v_mov_b32_e32 v2, 0
	s_addc_u32 s43, s43, s5
	s_mov_b32 s12, 0
	v_mov_b32_e32 v3, v2
	v_mov_b32_e32 v4, v2
	v_mov_b32_e32 v5, v2
	v_mov_b32_e32 v6, v2
	v_mov_b32_e32 v7, v2
	v_mov_b32_e32 v8, v2
	v_mov_b32_e32 v9, v2
	v_mov_b32_e32 v18, v2
	v_mov_b32_e32 v19, v2
	v_mov_b32_e32 v20, v2
	v_mov_b32_e32 v21, v2
	v_mov_b32_e32 v22, v2
	v_mov_b32_e32 v23, v2
	v_mov_b32_e32 v24, v2
	v_mov_b32_e32 v25, v2
	v_mov_b32_e32 v34, v2
	v_mov_b32_e32 v35, v2
	v_mov_b32_e32 v36, v2
	v_mov_b32_e32 v37, v2
	v_mov_b32_e32 v38, v2
	v_mov_b32_e32 v39, v2
	v_mov_b32_e32 v40, v2
	v_mov_b32_e32 v41, v2
	v_mov_b32_e32 v50, v2
	v_mov_b32_e32 v51, v2
	v_mov_b32_e32 v52, v2
	v_mov_b32_e32 v53, v2
	v_mov_b32_e32 v54, v2
	v_mov_b32_e32 v55, v2
	v_mov_b32_e32 v56, v2
	v_mov_b32_e32 v57, v2
	v_mov_b32_e32 v10, v2
	v_mov_b32_e32 v11, v2
	v_mov_b32_e32 v12, v2
	v_mov_b32_e32 v13, v2
	v_mov_b32_e32 v14, v2
	v_mov_b32_e32 v15, v2
	v_mov_b32_e32 v16, v2
	v_mov_b32_e32 v17, v2
	v_mov_b32_e32 v26, v2
	v_mov_b32_e32 v27, v2
	v_mov_b32_e32 v28, v2
	v_mov_b32_e32 v29, v2
	v_mov_b32_e32 v30, v2
	v_mov_b32_e32 v31, v2
	v_mov_b32_e32 v32, v2
	v_mov_b32_e32 v33, v2
	v_mov_b32_e32 v42, v2
	v_mov_b32_e32 v43, v2
	v_mov_b32_e32 v44, v2
	v_mov_b32_e32 v45, v2
	v_mov_b32_e32 v46, v2
	v_mov_b32_e32 v47, v2
	v_mov_b32_e32 v48, v2
	v_mov_b32_e32 v49, v2
	v_mov_b32_e32 v58, v2
	v_mov_b32_e32 v59, v2
	v_mov_b32_e32 v60, v2
	v_mov_b32_e32 v61, v2
	v_mov_b32_e32 v62, v2
	v_mov_b32_e32 v63, v2
	v_mov_b32_e32 v64, v2
	v_mov_b32_e32 v65, v2
	v_mov_b32_e32 v66, v2
	v_mov_b32_e32 v67, v2
	v_mov_b32_e32 v68, v2
	v_mov_b32_e32 v69, v2
	v_mov_b32_e32 v70, v2
	v_mov_b32_e32 v71, v2
	v_mov_b32_e32 v72, v2
	v_mov_b32_e32 v73, v2
	v_mov_b32_e32 v82, v2
	v_mov_b32_e32 v83, v2
	v_mov_b32_e32 v84, v2
	v_mov_b32_e32 v85, v2
	v_mov_b32_e32 v86, v2
	v_mov_b32_e32 v87, v2
	v_mov_b32_e32 v88, v2
	v_mov_b32_e32 v89, v2
	v_mov_b32_e32 v98, v2
	v_mov_b32_e32 v99, v2
	v_mov_b32_e32 v100, v2
	v_mov_b32_e32 v101, v2
	v_mov_b32_e32 v102, v2
	v_mov_b32_e32 v103, v2
	v_mov_b32_e32 v104, v2
	v_mov_b32_e32 v105, v2
	v_mov_b32_e32 v114, v2
	v_mov_b32_e32 v115, v2
	v_mov_b32_e32 v116, v2
	v_mov_b32_e32 v117, v2
	v_mov_b32_e32 v118, v2
	v_mov_b32_e32 v119, v2
	v_mov_b32_e32 v120, v2
	v_mov_b32_e32 v121, v2
	v_mov_b32_e32 v74, v2
	v_mov_b32_e32 v75, v2
	v_mov_b32_e32 v76, v2
	v_mov_b32_e32 v77, v2
	v_mov_b32_e32 v78, v2
	v_mov_b32_e32 v79, v2
	v_mov_b32_e32 v80, v2
	v_mov_b32_e32 v81, v2
	v_mov_b32_e32 v90, v2
	v_mov_b32_e32 v91, v2
	v_mov_b32_e32 v92, v2
	v_mov_b32_e32 v93, v2
	v_mov_b32_e32 v94, v2
	v_mov_b32_e32 v95, v2
	v_mov_b32_e32 v96, v2
	v_mov_b32_e32 v97, v2
	v_mov_b32_e32 v106, v2
	v_mov_b32_e32 v107, v2
	v_mov_b32_e32 v108, v2
	v_mov_b32_e32 v109, v2
	v_mov_b32_e32 v110, v2
	v_mov_b32_e32 v111, v2
	v_mov_b32_e32 v112, v2
	v_mov_b32_e32 v113, v2
	v_mov_b32_e32 v122, v2
	v_mov_b32_e32 v123, v2
	v_mov_b32_e32 v124, v2
	v_mov_b32_e32 v125, v2
	v_mov_b32_e32 v126, v2
	v_mov_b32_e32 v127, v2
	v_mov_b32_e32 v128, v2
	v_mov_b32_e32 v129, v2
	s_branch .Lpeel400_401
.Lpeel400_401:
	s_cmp_lg_u32 s69, s12
	s_cselect_b64 s[2:3], -1, 0
	s_cmp_eq_u32 s69, s12
	s_mov_b64 s[50:51], s[8:9]
	s_cbranch_scc1 .Lpeel400_403
	s_add_u32 s50, s6, s44
	s_addc_u32 s51, s7, s45

; #define PG8_STAGE(bufoff, gbase, voff) do { _Pragma("unroll") for (int _i = 0; _i < 2; ++_i) \
;         __builtin_amdgcn_global_load_lds((const unsigned*)((const char*)(gbase) + (voff)[_i]), (LAS unsigned*)(lds + (bufoff) + ldsw + _i * 8192), 16, 0, 0); } while (0)
; #define PG8_LDA(dst, b, h) do { _Pragma("unroll") for (int m = 0; m < 4; ++m) _Pragma("unroll") for (int k = 0; k < 2; ++k) dst[m][k] = *(const LAS bf16x8*)(lds + PG8_SA(b, h) + aoff + m * 2048 + k * 1024); } while (0)
; #define PG8_LDB(dst, b, h) do { _Pragma("unroll") for (int n = 0; n < 2; ++n) _Pragma("unroll") for (int k = 0; k < 2; ++k) dst[n][k] = *(const LAS bf16x8*)(lds + PG8_SB(b, h) + boff + n * 2048 + k * 1024); } while (0)
; #define PG8_MMA(ai, bj, At, Bt) do { __builtin_amdgcn_s_setprio(1); _Pragma("unroll") for (int m = 0; m < 4; ++m) _Pragma("unroll") for (int n = 0; n < 2; ++n) _Pragma("unroll") for (int k = 0; k < 2; ++k) \
;         acc[ai][bj][m][n] = __builtin_amdgcn_mfma_f32_16x16x32_bf16(Bt[n][k], At[m][k], acc[ai][bj][m][n], 0, 0, 0); __builtin_amdgcn_s_setprio(0); } while (0)
; #define PG8_WAIT_V(n) asm volatile("s_waitcnt vmcnt(" #n ")" ::: "memory")
; #define PG8_WAIT_L(n) asm volatile("s_waitcnt lgkmcnt(" #n ")" ::: "memory")
; #define PG8_BAR __builtin_amdgcn_s_barrier()
; #define PG8_SCHED __builtin_amdgcn_sched_barrier(0)
; template <int MODE> __device__ __forceinline__ void gemm_phase(LAS unsigned char* lds, const GD& g, const int tid) {
;     ...
;         for (int t = 0; t < nt; t += 2) {
;             const bool last = (t == nt - 2);
;             const char* a1 = cA + (size_t)(t + 1) * kstA;
;             const char* a2 = last ? nA : cA + (size_t)(t + 2) * kstA; const char* b2 = last ? nB : cB + (size_t)(t + 2) * kstB;
;             const char* a3 = a2 + kstA; const char* b3 = b2 + kstB;
;             PG8_LDB(B0, 0, 0); PG8_LDB(B1, 0, 1); PG8_SCHED; PG8_LDA(At, 0, 0); PG8_STAGE(PG8_SA(1, 1), a1 + hsA, voffA);
;             PG8_WAIT_V(8); PG8_WAIT_L(0); PG8_BAR; PG8_MMA(0, 0, At, B0); PG8_MMA(0, 1, At, B1); PG8_BAR; PG8_SCHED;
;             PG8_LDA(At, 0, 1); PG8_STAGE(PG8_SB(0, 0), b2, voffB); PG8_STAGE(PG8_SB(0, 1), b2 + hsB, voffB); PG8_STAGE(PG8_SA(0, 0), a2, voffA);
;             PG8_WAIT_V(8); PG8_WAIT_L(0); PG8_BAR; PG8_MMA(1, 0, At, B0); PG8_MMA(1, 1, At, B1); PG8_BAR; PG8_SCHED;
.Lpeel400_400:
	s_add_i32 s12, s12, 2
	s_add_u32 s2, s50, s20
	s_addc_u32 s3, s51, s21
	s_add_i32 s13, 0, 0x10000
	v_add_u32_e32 v1, s13, v173
	s_add_i32 s17, 0, 0x14000
	ds_read_b128 v[130:133], v1
	ds_read_b128 v[134:137], v1 offset:1024
	ds_read_b128 v[138:141], v1 offset:2048
	ds_read_b128 v[142:145], v1 offset:3072
	v_add_u32_e32 v1, s17, v173
	ds_read_b128 v[158:161], v1
	ds_read_b128 v[178:181], v1 offset:1024
	ds_read_b128 v[182:185], v1 offset:2048
	ds_read_b128 v[186:189], v1 offset:3072
	v_lshl_add_u64 v[162:163], s[6:7], 0, v[156:157]
	s_add_i32 m0, s27, 0xc000
	ds_read_b128 v[190:193], v176
	ds_read_b128 v[196:199], v176 offset:1024
	ds_read_b128 v[204:207], v176 offset:2048
	ds_read_b128 v[220:223], v176 offset:3072
	ds_read_b128 v[224:227], v176 offset:4096
	ds_read_b128 v[228:231], v176 offset:5120
	ds_read_b128 v[232:235], v176 offset:6144
	ds_read_b128 v[236:239], v176 offset:7168
	global_load_lds_dwordx4 v[162:163], off
	v_lshl_add_u64 v[162:163], s[6:7], 0, v[154:155]
	s_add_i32 m0, s27, 0xe000
	s_nop 0
	global_load_lds_dwordx4 v[162:163], off
	s_waitcnt vmcnt(32)
	s_waitcnt lgkmcnt(0)
	s_barrier
	s_setprio 1
	s_waitcnt lgkmcnt(0)
	v_mfma_f32_16x16x32_bf16 v[126:129], v[130:133], v[190:193], v[126:129]
	v_mfma_f32_16x16x32_bf16 v[122:125], v[138:141], v[190:193], v[122:125]
	v_mfma_f32_16x16x32_bf16 v[110:113], v[130:133], v[204:207], v[110:113]
	v_mfma_f32_16x16x32_bf16 v[106:109], v[138:141], v[204:207], v[106:109]
	v_mfma_f32_16x16x32_bf16 v[94:97], v[130:133], v[224:227], v[94:97]
	v_mfma_f32_16x16x32_bf16 v[90:93], v[138:141], v[224:227], v[90:93]
	v_mfma_f32_16x16x32_bf16 v[78:81], v[130:133], v[232:235], v[78:81]
	v_mfma_f32_16x16x32_bf16 v[74:77], v[138:141], v[232:235], v[74:77]
	v_mfma_f32_16x16x32_bf16 v[126:129], v[134:137], v[196:199], v[126:129]
	v_mfma_f32_16x16x32_bf16 v[122:125], v[142:145], v[196:199], v[122:125]
	v_mfma_f32_16x16x32_bf16 v[110:113], v[134:137], v[220:223], v[110:113]
	v_mfma_f32_16x16x32_bf16 v[106:109], v[142:145], v[220:223], v[106:109]
	v_mfma_f32_16x16x32_bf16 v[94:97], v[134:137], v[228:231], v[94:97]
	v_mfma_f32_16x16x32_bf16 v[90:93], v[142:145], v[228:231], v[90:93]
	v_mfma_f32_16x16x32_bf16 v[78:81], v[134:137], v[236:239], v[78:81]
	v_mfma_f32_16x16x32_bf16 v[74:77], v[142:145], v[236:239], v[74:77]
	s_setprio 0
	s_setprio 1
	v_mfma_f32_16x16x32_bf16 v[118:121], v[158:161], v[190:193], v[118:121]
	v_mfma_f32_16x16x32_bf16 v[114:117], v[182:185], v[190:193], v[114:117]
	v_mfma_f32_16x16x32_bf16 v[102:105], v[158:161], v[204:207], v[102:105]
	v_mfma_f32_16x16x32_bf16 v[98:101], v[182:185], v[204:207], v[98:101]
	v_mfma_f32_16x16x32_bf16 v[86:89], v[158:161], v[224:227], v[86:89]
	v_mfma_f32_16x16x32_bf16 v[82:85], v[182:185], v[224:227], v[82:85]
	v_mfma_f32_16x16x32_bf16 v[70:73], v[158:161], v[232:235], v[70:73]
	v_mfma_f32_16x16x32_bf16 v[66:69], v[182:185], v[232:235], v[66:69]
	v_mfma_f32_16x16x32_bf16 v[118:121], v[178:181], v[196:199], v[118:121]
	v_mfma_f32_16x16x32_bf16 v[114:117], v[186:189], v[196:199], v[114:117]
	v_mfma_f32_16x16x32_bf16 v[102:105], v[178:181], v[220:223], v[102:105]
	v_mfma_f32_16x16x32_bf16 v[98:101], v[186:189], v[220:223], v[98:101]
	v_mfma_f32_16x16x32_bf16 v[86:89], v[178:181], v[228:231], v[86:89]
	v_mfma_f32_16x16x32_bf16 v[82:85], v[186:189], v[228:231], v[82:85]
	v_mfma_f32_16x16x32_bf16 v[70:73], v[178:181], v[236:239], v[70:73]
	v_mfma_f32_16x16x32_bf16 v[66:69], v[186:189], v[236:239], v[66:69]
	s_setprio 0
	s_barrier
	s_add_i32 s13, s13, s25
	v_lshl_add_u64 v[162:163], s[48:49], 0, v[148:149]
	s_mov_b32 m0, s13
	ds_read_b128 v[190:193], v176 offset:16384
	ds_read_b128 v[196:199], v176 offset:17408
	ds_read_b128 v[204:207], v176 offset:18432
	ds_read_b128 v[220:223], v176 offset:19456
	ds_read_b128 v[224:227], v176 offset:20480
	ds_read_b128 v[228:231], v176 offset:21504
	ds_read_b128 v[232:235], v176 offset:22528
	ds_read_b128 v[236:239], v176 offset:23552
	global_load_lds_dwordx4 v[162:163], off
	s_add_i32 m0, s13, 0x2000
	s_add_u32 s14, s48, s78
	v_lshl_add_u64 v[162:163], s[48:49], 0, v[152:153]
	s_addc_u32 s15, s49, s79
	s_add_i32 s13, s17, s25
	global_load_lds_dwordx4 v[162:163], off
	v_lshl_add_u64 v[162:163], s[14:15], 0, v[148:149]
	s_mov_b32 m0, s13
	s_nop 0
	global_load_lds_dwordx4 v[162:163], off
	v_lshl_add_u64 v[162:163], s[14:15], 0, v[152:153]
	s_add_i32 m0, s13, 0x2000
	s_nop 0
	global_load_lds_dwordx4 v[162:163], off
	v_lshl_add_u64 v[162:163], s[50:51], 0, v[146:147]
	s_mov_b32 m0, s27
	s_nop 0
	global_load_lds_dwordx4 v[162:163], off
	v_lshl_add_u64 v[162:163], s[50:51], 0, v[150:151]
	s_mov_b32 m0, s64
	s_nop 0
	global_load_lds_dwordx4 v[162:163], off
	s_waitcnt vmcnt(32)
	s_waitcnt lgkmcnt(0)
	s_barrier
; #define PG8_STAGE(bufoff, gbase, voff) do { _Pragma("unroll") for (int _i = 0; _i < 2; ++_i) \
;         __builtin_amdgcn_global_load_lds((const unsigned*)((const char*)(gbase) + (voff)[_i]), (LAS unsigned*)(lds + (bufoff) + ldsw + _i * 8192), 16, 0, 0); } while (0)
; #define PG8_LDA(dst, b, h) do { _Pragma("unroll") for (int m = 0; m < 4; ++m) _Pragma("unroll") for (int k = 0; k < 2; ++k) dst[m][k] = *(const LAS bf16x8*)(lds + PG8_SA(b, h) + aoff + m * 2048 + k * 1024); } while (0)
; #define PG8_LDB(dst, b, h) do { _Pragma("unroll") for (int n = 0; n < 2; ++n) _Pragma("unroll") for (int k = 0; k < 2; ++k) dst[n][k] = *(const LAS bf16x8*)(lds + PG8_SB(b, h) + boff + n * 2048 + k * 1024); } while (0)
; #define PG8_MMA(ai, bj, At, Bt) do { __builtin_amdgcn_s_setprio(1); _Pragma("unroll") for (int m = 0; m < 4; ++m) _Pragma("unroll") for (int n = 0; n < 2; ++n) _Pragma("unroll") for (int k = 0; k < 2; ++k) \
;         acc[ai][bj][m][n] = __builtin_amdgcn_mfma_f32_16x16x32_bf16(Bt[n][k], At[m][k], acc[ai][bj][m][n], 0, 0, 0); __builtin_amdgcn_s_setprio(0); } while (0)
; #define PG8_WAIT_V(n) asm volatile("s_waitcnt vmcnt(" #n ")" ::: "memory")
; #define PG8_WAIT_L(n) asm volatile("s_waitcnt lgkmcnt(" #n ")" ::: "memory")
; #define PG8_BAR __builtin_amdgcn_s_barrier()
; #define PG8_SCHED __builtin_amdgcn_sched_barrier(0)
; template <int MODE> __device__ __forceinline__ void gemm_phase(LAS unsigned char* lds, const GD& g, const int tid) {
;     ...
;             PG8_WAIT_V(8); PG8_WAIT_L(0); PG8_BAR; PG8_MMA(1, 0, At, B0); PG8_MMA(1, 1, At, B1); PG8_BAR; PG8_SCHED;
;             PG8_LDB(B0, 1, 0); PG8_LDB(B1, 1, 1); PG8_SCHED; PG8_LDA(At, 1, 0); PG8_STAGE(PG8_SA(0, 1), a2 + hsA, voffA);
;             PG8_WAIT_V(8); PG8_WAIT_L(0); PG8_BAR; PG8_MMA(0, 0, At, B0); PG8_MMA(0, 1, At, B1); PG8_BAR; PG8_SCHED;
	s_setprio 1
	s_waitcnt lgkmcnt(0)
	v_mfma_f32_16x16x32_bf16 v[62:65], v[130:133], v[190:193], v[62:65]
	v_mfma_f32_16x16x32_bf16 v[58:61], v[138:141], v[190:193], v[58:61]
	v_mfma_f32_16x16x32_bf16 v[46:49], v[130:133], v[204:207], v[46:49]
	v_mfma_f32_16x16x32_bf16 v[42:45], v[138:141], v[204:207], v[42:45]
	v_mfma_f32_16x16x32_bf16 v[30:33], v[130:133], v[224:227], v[30:33]
	v_mfma_f32_16x16x32_bf16 v[26:29], v[138:141], v[224:227], v[26:29]
	v_mfma_f32_16x16x32_bf16 v[14:17], v[130:133], v[232:235], v[14:17]
	v_mfma_f32_16x16x32_bf16 v[10:13], v[138:141], v[232:235], v[10:13]
	v_mfma_f32_16x16x32_bf16 v[62:65], v[134:137], v[196:199], v[62:65]
	v_mfma_f32_16x16x32_bf16 v[58:61], v[142:145], v[196:199], v[58:61]
	v_mfma_f32_16x16x32_bf16 v[46:49], v[134:137], v[220:223], v[46:49]
	v_mfma_f32_16x16x32_bf16 v[42:45], v[142:145], v[220:223], v[42:45]
	v_mfma_f32_16x16x32_bf16 v[30:33], v[134:137], v[228:231], v[30:33]
	v_mfma_f32_16x16x32_bf16 v[26:29], v[142:145], v[228:231], v[26:29]
	v_mfma_f32_16x16x32_bf16 v[14:17], v[134:137], v[236:239], v[14:17]
	v_mfma_f32_16x16x32_bf16 v[10:13], v[142:145], v[236:239], v[10:13]
	s_setprio 0
	s_setprio 1
	v_mfma_f32_16x16x32_bf16 v[54:57], v[158:161], v[190:193], v[54:57]
	v_mfma_f32_16x16x32_bf16 v[50:53], v[182:185], v[190:193], v[50:53]
	v_mfma_f32_16x16x32_bf16 v[38:41], v[158:161], v[204:207], v[38:41]
	v_mfma_f32_16x16x32_bf16 v[34:37], v[182:185], v[204:207], v[34:37]
	v_mfma_f32_16x16x32_bf16 v[22:25], v[158:161], v[224:227], v[22:25]
	v_mfma_f32_16x16x32_bf16 v[18:21], v[182:185], v[224:227], v[18:21]
	v_mfma_f32_16x16x32_bf16 v[6:9], v[158:161], v[232:235], v[6:9]
	v_mfma_f32_16x16x32_bf16 v[2:5], v[182:185], v[232:235], v[2:5]
	v_mfma_f32_16x16x32_bf16 v[54:57], v[178:181], v[196:199], v[54:57]
	v_mfma_f32_16x16x32_bf16 v[50:53], v[186:189], v[196:199], v[50:53]
	v_mfma_f32_16x16x32_bf16 v[38:41], v[178:181], v[220:223], v[38:41]
	v_mfma_f32_16x16x32_bf16 v[34:37], v[186:189], v[220:223], v[34:37]
	v_mfma_f32_16x16x32_bf16 v[22:25], v[178:181], v[228:231], v[22:25]
	v_mfma_f32_16x16x32_bf16 v[18:21], v[186:189], v[228:231], v[18:21]
	v_mfma_f32_16x16x32_bf16 v[6:9], v[178:181], v[236:239], v[6:9]
	v_mfma_f32_16x16x32_bf16 v[2:5], v[186:189], v[236:239], v[2:5]
	s_setprio 0
	s_barrier
	s_add_i32 s13, 0, 0x18000
	v_add_u32_e32 v1, s13, v173
	s_add_i32 s17, 0, 0x1c000
	ds_read_b128 v[130:133], v1
	ds_read_b128 v[134:137], v1 offset:1024
	ds_read_b128 v[138:141], v1 offset:2048
	ds_read_b128 v[142:145], v1 offset:3072
	v_add_u32_e32 v1, s17, v173
	ds_read_b128 v[158:161], v1
	ds_read_b128 v[178:181], v1 offset:1024
	ds_read_b128 v[182:185], v1 offset:2048
	ds_read_b128 v[186:189], v1 offset:3072
	s_add_u32 s14, s50, s76
	s_addc_u32 s15, s51, s77
	s_mov_b32 m0, s65
	v_lshl_add_u64 v[162:163], s[14:15], 0, v[146:147]
	ds_read_b128 v[190:193], v176 offset:32768
	ds_read_b128 v[196:199], v176 offset:33792
	ds_read_b128 v[204:207], v176 offset:34816
	ds_read_b128 v[220:223], v176 offset:35840
	ds_read_b128 v[224:227], v176 offset:36864
	ds_read_b128 v[228:231], v176 offset:37888
	ds_read_b128 v[232:235], v176 offset:38912
	ds_read_b128 v[236:239], v176 offset:39936
	global_load_lds_dwordx4 v[162:163], off
	v_lshl_add_u64 v[162:163], s[14:15], 0, v[150:151]
	s_mov_b32 m0, s68
	s_nop 0
	global_load_lds_dwordx4 v[162:163], off
	s_waitcnt vmcnt(8)
	s_waitcnt lgkmcnt(0)
	s_barrier
	s_setprio 1
	s_waitcnt lgkmcnt(0)
	v_mfma_f32_16x16x32_bf16 v[126:129], v[130:133], v[190:193], v[126:129]
	v_mfma_f32_16x16x32_bf16 v[122:125], v[138:141], v[190:193], v[122:125]
	v_mfma_f32_16x16x32_bf16 v[110:113], v[130:133], v[204:207], v[110:113]
	v_mfma_f32_16x16x32_bf16 v[106:109], v[138:141], v[204:207], v[106:109]
	v_mfma_f32_16x16x32_bf16 v[94:97], v[130:133], v[224:227], v[94:97]
	v_mfma_f32_16x16x32_bf16 v[90:93], v[138:141], v[224:227], v[90:93]
	v_mfma_f32_16x16x32_bf16 v[78:81], v[130:133], v[232:235], v[78:81]
	v_mfma_f32_16x16x32_bf16 v[74:77], v[138:141], v[232:235], v[74:77]
	v_mfma_f32_16x16x32_bf16 v[126:129], v[134:137], v[196:199], v[126:129]
	v_mfma_f32_16x16x32_bf16 v[122:125], v[142:145], v[196:199], v[122:125]
	v_mfma_f32_16x16x32_bf16 v[110:113], v[134:137], v[220:223], v[110:113]
	v_mfma_f32_16x16x32_bf16 v[106:109], v[142:145], v[220:223], v[106:109]
	v_mfma_f32_16x16x32_bf16 v[94:97], v[134:137], v[228:231], v[94:97]
	v_mfma_f32_16x16x32_bf16 v[90:93], v[142:145], v[228:231], v[90:93]
	v_mfma_f32_16x16x32_bf16 v[78:81], v[134:137], v[236:239], v[78:81]
	v_mfma_f32_16x16x32_bf16 v[74:77], v[142:145], v[236:239], v[74:77]
	s_setprio 0
	s_setprio 1
	v_mfma_f32_16x16x32_bf16 v[118:121], v[158:161], v[190:193], v[118:121]
	v_mfma_f32_16x16x32_bf16 v[114:117], v[182:185], v[190:193], v[114:117]
	v_mfma_f32_16x16x32_bf16 v[102:105], v[158:161], v[204:207], v[102:105]
	v_mfma_f32_16x16x32_bf16 v[98:101], v[182:185], v[204:207], v[98:101]
	v_mfma_f32_16x16x32_bf16 v[86:89], v[158:161], v[224:227], v[86:89]
	v_mfma_f32_16x16x32_bf16 v[82:85], v[182:185], v[224:227], v[82:85]
	v_mfma_f32_16x16x32_bf16 v[70:73], v[158:161], v[232:235], v[70:73]
	v_mfma_f32_16x16x32_bf16 v[66:69], v[182:185], v[232:235], v[66:69]
	v_mfma_f32_16x16x32_bf16 v[118:121], v[178:181], v[196:199], v[118:121]
	v_mfma_f32_16x16x32_bf16 v[114:117], v[186:189], v[196:199], v[114:117]
	v_mfma_f32_16x16x32_bf16 v[102:105], v[178:181], v[220:223], v[102:105]
	v_mfma_f32_16x16x32_bf16 v[98:101], v[186:189], v[220:223], v[98:101]
	v_mfma_f32_16x16x32_bf16 v[86:89], v[178:181], v[228:231], v[86:89]
	v_mfma_f32_16x16x32_bf16 v[82:85], v[186:189], v[228:231], v[82:85]
	v_mfma_f32_16x16x32_bf16 v[70:73], v[178:181], v[236:239], v[70:73]
	v_mfma_f32_16x16x32_bf16 v[66:69], v[186:189], v[236:239], v[66:69]
	s_setprio 0
	s_barrier
; #define PG8_STAGE(bufoff, gbase, voff) do { _Pragma("unroll") for (int _i = 0; _i < 2; ++_i) \
;         __builtin_amdgcn_global_load_lds((const unsigned*)((const char*)(gbase) + (voff)[_i]), (LAS unsigned*)(lds + (bufoff) + ldsw + _i * 8192), 16, 0, 0); } while (0)
; #define PG8_LDA(dst, b, h) do { _Pragma("unroll") for (int m = 0; m < 4; ++m) _Pragma("unroll") for (int k = 0; k < 2; ++k) dst[m][k] = *(const LAS bf16x8*)(lds + PG8_SA(b, h) + aoff + m * 2048 + k * 1024); } while (0)
; #define PG8_MMA(ai, bj, At, Bt) do { __builtin_amdgcn_s_setprio(1); _Pragma("unroll") for (int m = 0; m < 4; ++m) _Pragma("unroll") for (int n = 0; n < 2; ++n) _Pragma("unroll") for (int k = 0; k < 2; ++k) \
;         acc[ai][bj][m][n] = __builtin_amdgcn_mfma_f32_16x16x32_bf16(Bt[n][k], At[m][k], acc[ai][bj][m][n], 0, 0, 0); __builtin_amdgcn_s_setprio(0); } while (0)
; #define PG8_WAIT_V(n) asm volatile("s_waitcnt vmcnt(" #n ")" ::: "memory")
; #define PG8_WAIT_L(n) asm volatile("s_waitcnt lgkmcnt(" #n ")" ::: "memory")
; #define PG8_BAR __builtin_amdgcn_s_barrier()
; #define PG8_SCHED __builtin_amdgcn_sched_barrier(0)
; template <int MODE> __device__ __forceinline__ void gemm_phase(LAS unsigned char* lds, const GD& g, const int tid) {
;     ...
;             PG8_LDA(At, 1, 1); PG8_STAGE(PG8_SB(1, 0), b3, voffB); PG8_STAGE(PG8_SB(1, 1), b3 + hsB, voffB); PG8_STAGE(PG8_SA(1, 0), a3, voffA);
;             PG8_WAIT_V(8); PG8_WAIT_L(0); PG8_BAR; PG8_MMA(1, 0, At, B0); PG8_MMA(1, 1, At, B1); PG8_BAR; PG8_SCHED;
;         }
	s_add_u32 s14, s48, s22
	s_addc_u32 s15, s49, s23
	s_add_i32 s13, s13, s25
	v_lshl_add_u64 v[162:163], s[14:15], 0, v[148:149]
	s_mov_b32 m0, s13
	ds_read_b128 v[190:193], v176 offset:49152
	ds_read_b128 v[196:199], v176 offset:50176
	ds_read_b128 v[204:207], v176 offset:51200
	ds_read_b128 v[220:223], v176 offset:52224
	ds_read_b128 v[224:227], v176 offset:53248
	ds_read_b128 v[228:231], v176 offset:54272
	ds_read_b128 v[232:235], v176 offset:55296
	ds_read_b128 v[236:239], v176 offset:56320
	global_load_lds_dwordx4 v[162:163], off
	s_add_i32 m0, s13, 0x2000
	v_lshl_add_u64 v[162:163], s[14:15], 0, v[152:153]
	s_add_u32 s14, s14, s78
	s_addc_u32 s15, s15, s79
	s_add_i32 s13, s17, s25
	global_load_lds_dwordx4 v[162:163], off
	v_lshl_add_u64 v[162:163], s[14:15], 0, v[148:149]
	s_mov_b32 m0, s13
	s_nop 0
	global_load_lds_dwordx4 v[162:163], off
	v_lshl_add_u64 v[162:163], s[14:15], 0, v[152:153]
	s_add_i32 m0, s13, 0x2000
	s_nop 0
	global_load_lds_dwordx4 v[162:163], off
	v_lshl_add_u64 v[162:163], s[2:3], 0, v[146:147]
	s_mov_b32 m0, s82
	s_nop 0
	global_load_lds_dwordx4 v[162:163], off
	v_lshl_add_u64 v[162:163], s[2:3], 0, v[150:151]
	s_mov_b32 m0, s83
	s_nop 0
	global_load_lds_dwordx4 v[162:163], off
	s_waitcnt vmcnt(8)
	s_waitcnt lgkmcnt(0)
	s_barrier
	s_setprio 1
	s_waitcnt lgkmcnt(0)
	v_mfma_f32_16x16x32_bf16 v[62:65], v[130:133], v[190:193], v[62:65]
	v_mfma_f32_16x16x32_bf16 v[58:61], v[138:141], v[190:193], v[58:61]
	v_mfma_f32_16x16x32_bf16 v[46:49], v[130:133], v[204:207], v[46:49]
	v_mfma_f32_16x16x32_bf16 v[42:45], v[138:141], v[204:207], v[42:45]
	v_mfma_f32_16x16x32_bf16 v[30:33], v[130:133], v[224:227], v[30:33]
	v_mfma_f32_16x16x32_bf16 v[26:29], v[138:141], v[224:227], v[26:29]
	v_mfma_f32_16x16x32_bf16 v[14:17], v[130:133], v[232:235], v[14:17]
	v_mfma_f32_16x16x32_bf16 v[10:13], v[138:141], v[232:235], v[10:13]
	v_mfma_f32_16x16x32_bf16 v[62:65], v[134:137], v[196:199], v[62:65]
	v_mfma_f32_16x16x32_bf16 v[58:61], v[142:145], v[196:199], v[58:61]
	v_mfma_f32_16x16x32_bf16 v[46:49], v[134:137], v[220:223], v[46:49]
	v_mfma_f32_16x16x32_bf16 v[42:45], v[142:145], v[220:223], v[42:45]
	v_mfma_f32_16x16x32_bf16 v[30:33], v[134:137], v[228:231], v[30:33]
	v_mfma_f32_16x16x32_bf16 v[26:29], v[142:145], v[228:231], v[26:29]
	v_mfma_f32_16x16x32_bf16 v[14:17], v[134:137], v[236:239], v[14:17]
	v_mfma_f32_16x16x32_bf16 v[10:13], v[142:145], v[236:239], v[10:13]
	s_setprio 0
	s_setprio 1
	v_mfma_f32_16x16x32_bf16 v[54:57], v[158:161], v[190:193], v[54:57]
	v_mfma_f32_16x16x32_bf16 v[50:53], v[182:185], v[190:193], v[50:53]
	v_mfma_f32_16x16x32_bf16 v[38:41], v[158:161], v[204:207], v[38:41]
	v_mfma_f32_16x16x32_bf16 v[34:37], v[182:185], v[204:207], v[34:37]
	v_mfma_f32_16x16x32_bf16 v[22:25], v[158:161], v[224:227], v[22:25]
	v_mfma_f32_16x16x32_bf16 v[18:21], v[182:185], v[224:227], v[18:21]
	v_mfma_f32_16x16x32_bf16 v[6:9], v[158:161], v[232:235], v[6:9]
	v_mfma_f32_16x16x32_bf16 v[2:5], v[182:185], v[232:235], v[2:5]
	v_mfma_f32_16x16x32_bf16 v[54:57], v[178:181], v[196:199], v[54:57]
	v_mfma_f32_16x16x32_bf16 v[50:53], v[186:189], v[196:199], v[50:53]
	v_mfma_f32_16x16x32_bf16 v[38:41], v[178:181], v[220:223], v[38:41]
	v_mfma_f32_16x16x32_bf16 v[34:37], v[186:189], v[220:223], v[34:37]
	v_mfma_f32_16x16x32_bf16 v[22:25], v[178:181], v[228:231], v[22:25]
	v_mfma_f32_16x16x32_bf16 v[18:21], v[186:189], v[228:231], v[18:21]
	v_mfma_f32_16x16x32_bf16 v[6:9], v[178:181], v[236:239], v[6:9]
	v_mfma_f32_16x16x32_bf16 v[2:5], v[186:189], v[236:239], v[2:5]
	s_setprio 0
	s_barrier
	s_add_u32 s42, s42, s4
	s_addc_u32 s43, s43, s5
	s_add_u32 s6, s6, s44
	s_addc_u32 s7, s7, s45
	s_cmp_ge_i32 s12, s36
	s_cbranch_scc1 .LBB0_406
	s_branch .LBB0_401
